# seams 6-9 use 4-block group barriers (panel-local P7/P10 rows; XCC-consistency predicate with grid-barrier fallback) and a 4-class 16us start stagger at out-proj so memory-bound epilogues/norms overla
# speedup vs baseline: 1.0162x; 1.0162x over previous
_Z4mega6Params:
	s_mov_b32 s32, 0
	s_load_dwordx8 s[20:27], s[0:1], 0x120
	s_load_dwordx8 s[4:11], s[0:1], 0x100
	s_load_dword s97, s[0:1], 0x140
	v_and_b32_e32 v144, 0x3ff, v0
	s_mov_b32 s3, s2
	v_cmp_gt_u32_e64 s[18:19], 4, v144
	s_waitcnt lgkmcnt(0)
	v_writelane_b32 v248, s4, 0
	s_nop 1
	v_writelane_b32 v248, s5, 1
	v_writelane_b32 v248, s6, 2
	v_writelane_b32 v248, s7, 3
	v_writelane_b32 v248, s8, 4
	v_writelane_b32 v248, s9, 5
	v_writelane_b32 v248, s10, 6
	v_writelane_b32 v248, s11, 7
	s_add_u32 s8, s0, 0x138
	s_addc_u32 s9, s1, 0
	s_and_saveexec_b64 s[4:5], s[18:19]
	v_lshl_add_u32 v1, v144, 2, 0
	v_add_u32_e32 v1, 0x23fe0, v1
	v_mov_b32_e32 v2, 0
	ds_write_b32 v1, v2
	s_or_b64 exec, exec, s[4:5]
	s_waitcnt lgkmcnt(0)
	s_barrier
	s_add_u32 s94, s22, 0x1be4c100
	s_getreg_b32 s2, hwreg(HW_REG_XCC_ID, 0, 4)
	s_addc_u32 s95, s23, 0
	s_and_b32 s96, s2, 15
	v_cmp_eq_u32_e64 s[4:5], 0, v144
	s_and_saveexec_b64 s[6:7], s[4:5]
	s_cbranch_execz .LBB0_5
	s_mov_b64 s[10:11], exec
	v_mbcnt_lo_u32_b32 v1, s10, 0
	v_mbcnt_hi_u32_b32 v1, s11, v1
	v_cmp_eq_u32_e32 vcc, 0, v1
	s_and_b64 s[12:13], exec, vcc
	s_mov_b64 exec, s[12:13]
	s_cbranch_execz .LBB0_5
	s_lshl_b32 s2, s96, 8
	s_bcnt1_i32_b64 s10, s[10:11]
	v_mov_b32_e32 v1, s2
	v_mov_b32_e32 v2, s10
	global_atomic_add v1, v2, s[94:95] offset:1024
	v_mov_b32_e32 v3, s3
	v_mov_b32_e32 v4, s96
	global_store_byte v3, v4, s[94:95]

.LBB0_1056:
	s_cmp_lt_i32 s24, 7
	s_cselect_b64 s[6:7], -1, 0
	s_and_b64 s[0:1], s[6:7], s[0:1]
	s_andn2_b64 vcc, exec, s[0:1]
	s_cbranch_vccnz .LBB0_1080
	s_cmpk_gt_i32 s3, 0x1ff
	v_readfirstlane_b32 s2, v144
	s_cbranch_scc1 .LBB0_1080
	s_add_u32 s8, s22, 0x1be4c100
	s_addc_u32 s9, s23, 0
	v_and_b32_e32 v0, 63, v144
	global_load_ubyte v1, v0, s[8:9] sc1
	global_load_ubyte v2, v0, s[8:9] offset:64 sc1
	global_load_ubyte v3, v0, s[8:9] offset:128 sc1
	global_load_ubyte v4, v0, s[8:9] offset:192 sc1
	s_waitcnt vmcnt(0)
	v_cmp_eq_u32_e32 vcc, v1, v2
	v_cmp_eq_u32_e64 s[10:11], v1, v3
	v_cmp_eq_u32_e64 s[12:13], v1, v4
	s_nop 3
	s_and_b64 s[10:11], s[10:11], s[12:13]
	s_and_b64 vcc, vcc, s[10:11]
	s_cmp_eq_u64 vcc, exec
	s_cselect_b32 s32, 1, 0
	s_cmp_eq_u32 s32, 0
	s_cbranch_scc1 .Lstag_done
	s_and_b32 s98, s3, 3
	s_cmp_eq_u32 s98, 0
	s_cbranch_scc1 .Lstag_done
.Lstag_loop:
	s_sleep 127
	s_sleep 127
	s_sleep 127
	s_sleep 127
	s_add_i32 s98, s98, -1
	s_cmp_lg_u32 s98, 0
	s_cbranch_scc1 .Lstag_loop
.Lstag_done:
	s_ashr_i32 s33, s3, 31
	s_lshr_b32 s6, s33, 29
	s_add_i32 s8, s3, s6
	s_and_b32 s6, s8, -8
	s_sub_i32 s10, s3, s6
	s_cmp_gt_i32 s10, -1
	s_cbranch_scc0 .LBB0_1060
	s_lshl_b32 s9, s10, 6
	s_cbranch_execz .LBB0_1061
	s_branch .LBB0_1062

.LBB0_1080:
	s_cmp_gt_i32 s25, 7
	s_cselect_b64 s[6:7], -1, 0
	s_and_b64 s[0:1], s[0:1], s[6:7]
	s_andn2_b64 vcc, exec, s[0:1]
	s_cbranch_vccnz .LBB0_1134
	s_cmp_lg_u32 s32, 0
	s_addc_u32 s32, s32, 0
	s_waitcnt vmcnt(0)
	s_waitcnt vmcnt(0) lgkmcnt(0)
	s_barrier
	s_and_saveexec_b64 s[0:1], s[4:5]
	s_cbranch_execz .LBB0_1133
	s_cmp_lg_u32 s32, 0
	s_cbranch_scc1 .Lgb6
	s_add_i32 s2, 0, 0x23fe0
	v_mov_b32_e32 v0, s2
	s_waitcnt vmcnt(0) expcnt(0) lgkmcnt(0)
	ds_read_b32 v2, v0
	s_add_i32 s2, 0, 0x23fe4
	v_mov_b32_e32 v0, s2
	ds_read_b32 v0, v0
	s_waitcnt lgkmcnt(1)
	v_cmp_ne_u32_e32 vcc, 0, v2
	s_cbranch_vccnz .LBB0_1097
	s_add_u32 s8, s22, 0x1be4c300
	s_addc_u32 s9, s23, 0
	s_add_u32 s10, s22, 0x1be4c500
	s_addc_u32 s11, s23, 0
	s_add_u32 s12, s22, 0x1be4c600
	s_addc_u32 s13, s23, 0
	s_add_u32 s14, s22, 0x1be4c700
	s_addc_u32 s15, s23, 0
	s_add_u32 s16, s22, 0x1be4c800
	s_addc_u32 s17, s23, 0
	s_add_u32 s18, s22, 0x1be4c900
	s_addc_u32 s19, s23, 0
	s_add_u32 s30, s22, 0x1be4ca00
	s_addc_u32 s31, s23, 0
	s_add_u32 s34, s22, 0x1be4cb00
	s_addc_u32 s35, s23, 0
	s_add_u32 s36, s22, 0x1be4cc00
	s_addc_u32 s37, s23, 0
	s_add_u32 s38, s22, 0x1be4cd00
	s_addc_u32 s39, s23, 0
	s_add_u32 s40, s22, 0x1be4ce00
	s_addc_u32 s41, s23, 0
	s_add_u32 s42, s22, 0x1be4cf00
	s_addc_u32 s43, s23, 0
	s_add_u32 s44, s22, 0x1be4d000
	s_addc_u32 s45, s23, 0
	s_add_u32 s46, s22, 0x1be4d100
	s_addc_u32 s47, s23, 0
	s_add_u32 s48, s22, 0x1be4d200
	s_addc_u32 s49, s23, 0
	s_add_u32 s50, s22, 0x1be4d300
	s_addc_u32 s51, s23, 0
	s_mul_i32 s2, s27, s97
	s_add_u32 s52, s22, 0x1be4d400
	s_mul_i32 s2, s2, s26
	s_addc_u32 s53, s23, 0
	s_mov_b32 s33, 1
	v_mov_b32_e32 v16, 0
	s_branch .LBB0_1085

.LBB0_1132:
	s_or_b64 exec, exec, s[12:13]
	s_waitcnt vmcnt(0)
	s_branch .LBB0_1133
.Lgb6:
	s_and_b32 s2, s3, 63
	s_lshl_b32 s2, s2, 2
	s_add_u32 s8, s22, 0x1be4c200
	s_addc_u32 s9, s23, 0
	s_add_u32 s8, s8, s2
	s_addc_u32 s9, s9, 0
	v_mov_b32_e32 v0, 0
	v_mov_b32_e32 v1, 1
	global_atomic_add v0, v1, s[8:9]
	s_lshl_b32 s2, s32, 2
	s_add_i32 s2, s2, -4
	s_mov_b32 s10, 0
.Lgb6_poll:
	global_load_dword v2, v0, s[8:9] sc1
	s_add_i32 s10, s10, 1
	s_waitcnt vmcnt(0)
	v_cmp_gt_u32_e32 vcc, s2, v2
	s_cmp_lt_u32 s10, 0x4000
	s_cselect_b64 s[12:13], -1, 0
	s_and_b64 vcc, vcc, s[12:13]
	s_cbranch_vccnz .Lgb6_poll
	buffer_inv sc1
	s_waitcnt vmcnt(0)

.LBB0_1134:
	s_cmp_lt_i32 s24, 8
	s_cselect_b64 s[0:1], -1, 0
	s_and_b64 s[0:1], s[0:1], s[6:7]
	s_andn2_b64 vcc, exec, s[0:1]
	s_cbranch_vccnz .LBB0_1139
	s_waitcnt vmcnt(0)
	v_and_b32_e32 v0, 60, v145
	s_and_b32 s98, s3, 7
	s_lshl_b32 s98, s98, 11
	s_bfe_u32 s99, s3, 0x30003
	s_lshl_b32 s99, s99, 8
	s_or_b32 s98, s98, s99
	s_lshr_b32 s99, s3, 6
	s_lshl_b32 s99, s99, 6
	s_or_b32 s98, s98, s99
	v_add_u32_e32 v12, s98, v0
	s_movk_i32 s2, 0x4000
	v_cmp_gt_i32_e32 vcc, s2, v12
	s_and_saveexec_b64 s[6:7], vcc
	s_cbranch_execz .LBB0_1138
	v_mbcnt_lo_u32_b32 v1, -1, 0
	v_mbcnt_hi_u32_b32 v1, -1, v1
	v_and_b32_e32 v2, 64, v1
	v_add_u32_e32 v2, 64, v2
	v_xor_b32_e32 v3, 32, v1
	v_cmp_lt_i32_e32 vcc, v3, v2
	v_lshlrev_b32_e32 v0, 2, v144
	s_waitcnt lgkmcnt(0)
	v_readlane_b32 s36, v248, 24
	v_cndmask_b32_e32 v3, v1, v3, vcc
	v_lshlrev_b32_e32 v176, 2, v3
	v_xor_b32_e32 v3, 16, v1
	v_cmp_lt_i32_e32 vcc, v3, v2
	v_and_b32_e32 v0, 0xfc, v0
	v_readlane_b32 s50, v248, 38
	v_cndmask_b32_e32 v3, v1, v3, vcc
	v_lshlrev_b32_e32 v177, 2, v3
	v_xor_b32_e32 v3, 8, v1
	v_cmp_lt_i32_e32 vcc, v3, v2
	v_readlane_b32 s51, v248, 39
	v_mov_b32_e32 v15, 0
	v_cndmask_b32_e32 v3, v1, v3, vcc
	v_lshlrev_b32_e32 v178, 2, v3
	v_xor_b32_e32 v3, 4, v1
	v_cmp_lt_i32_e32 vcc, v3, v2
	v_or_b32_e32 v8, 0x400, v0
	v_lshlrev_b32_e32 v14, 2, v0
	s_mov_b64 s[14:15], s[50:51]
	v_cndmask_b32_e32 v3, v1, v3, vcc
	v_or_b32_e32 v10, 0x500, v0
	v_lshl_add_u64 v[16:17], s[14:15], 0, v[14:15]
	v_lshlrev_b32_e32 v14, 2, v8
	v_lshlrev_b32_e32 v179, 2, v3
	v_xor_b32_e32 v3, 2, v1
	v_or_b32_e32 v40, 0x600, v0
	v_lshl_add_u64 v[18:19], s[14:15], 0, v[14:15]
	v_lshlrev_b32_e32 v14, 2, v10
	v_cmp_lt_i32_e32 vcc, v3, v2
	v_or_b32_e32 v42, 0x700, v0
	v_lshl_add_u64 v[20:21], s[14:15], 0, v[14:15]
	v_lshlrev_b32_e32 v14, 2, v40
	v_cndmask_b32_e32 v3, v1, v3, vcc
	v_lshl_add_u64 v[22:23], s[14:15], 0, v[14:15]
	v_lshlrev_b32_e32 v14, 2, v42
	v_lshlrev_b32_e32 v180, 2, v3
	v_xor_b32_e32 v3, 1, v1
	v_lshl_add_u64 v[24:25], s[14:15], 0, v[14:15]
	v_lshlrev_b32_e32 v14, 1, v0
	v_cmp_lt_i32_e32 vcc, v3, v2
	v_lshl_add_u64 v[28:29], s[22:23], 0, v[14:15]
	s_mov_b64 s[10:11], 0x16a00000
	s_add_u32 s8, s22, 0x1bd60000
	v_cndmask_b32_e32 v1, v1, v3, vcc
	v_or_b32_e32 v2, 0x100, v0
	v_or_b32_e32 v4, 0x200, v0
	v_or_b32_e32 v6, 0x300, v0
	v_lshl_add_u64 v[26:27], v[28:29], 0, s[10:11]
	s_mov_b64 s[10:11], 0x5e00000
	s_mov_b32 s28, 0x358637bd
	s_addc_u32 s9, s23, 0
	v_lshlrev_b32_e32 v181, 2, v1
	s_lshl_b32 s2, s26, 5
	v_lshl_add_u64 v[28:29], v[28:29], 0, s[10:11]
	s_mov_b64 s[10:11], 0
	s_mov_b64 s[12:13], 0x6000
	s_mov_b64 s[14:15], 0x8000
	v_lshlrev_b32_e32 v30, 2, v0
	v_lshlrev_b32_e32 v32, 2, v2
	v_lshlrev_b32_e32 v34, 2, v4
	v_lshlrev_b32_e32 v36, 2, v6
	v_lshlrev_b32_e32 v14, 2, v8
	v_lshlrev_b32_e32 v38, 2, v10
	v_mov_b32_e32 v39, v15
	v_lshlrev_b32_e32 v40, 2, v40
	v_mov_b32_e32 v41, v15
	v_lshlrev_b32_e32 v42, 2, v42
	v_mov_b32_e32 v43, v15
	s_mov_b32 s16, 0x3a000000
	s_mov_b32 s17, 0x800000
	s_movk_i32 s18, 0x3fff
	v_mov_b32_e32 v31, v15
	v_mov_b32_e32 v33, v15
	v_mov_b32_e32 v35, v15
	v_mov_b32_e32 v37, v15
	v_mov_b64_e32 v[44:45], s[28:29]
	v_readlane_b32 s37, v248, 25
	v_readlane_b32 s38, v248, 26
	v_readlane_b32 s39, v248, 27
	v_readlane_b32 s40, v248, 28
	v_readlane_b32 s41, v248, 29
	v_readlane_b32 s42, v248, 30
	v_readlane_b32 s43, v248, 31
	v_readlane_b32 s44, v248, 32
	v_readlane_b32 s45, v248, 33
	v_readlane_b32 s46, v248, 34
	v_readlane_b32 s47, v248, 35
	v_readlane_b32 s48, v248, 36
	v_readlane_b32 s49, v248, 37
.LBB0_1137:
	v_ashrrev_i32_e32 v13, 31, v12
	v_lshlrev_b64 v[50:51], 12, v[12:13]
	v_lshl_add_u64 v[0:1], v[26:27], 0, v[50:51]
	global_load_dwordx2 v[56:57], v[0:1], off
	global_load_dwordx2 v[58:59], v[0:1], off offset:512
	global_load_dwordx2 v[64:65], v[0:1], off offset:1024
	global_load_dwordx2 v[66:67], v[0:1], off offset:1536
	global_load_dwordx2 v[74:75], v[0:1], off offset:2048
	global_load_dwordx2 v[80:81], v[0:1], off offset:2560
	global_load_dwordx2 v[82:83], v[0:1], off offset:3072
	global_load_dwordx2 v[84:85], v[0:1], off offset:3584
	v_add_u32_e32 v0, 1, v12
	v_ashrrev_i32_e32 v1, 31, v0
	v_lshlrev_b64 v[90:91], 12, v[0:1]
	v_lshl_add_u64 v[4:5], v[26:27], 0, v[90:91]
	global_load_dwordx2 v[86:87], v[4:5], off
	global_load_dwordx2 v[88:89], v[4:5], off offset:512
	global_load_dwordx2 v[92:93], v[4:5], off offset:1024
	global_load_dwordx4 v[0:3], v[16:17], off
	global_load_dwordx2 v[94:95], v[4:5], off offset:1536
	global_load_dwordx2 v[96:97], v[4:5], off offset:2048
	global_load_dwordx2 v[98:99], v[4:5], off offset:2560
	global_load_dwordx2 v[108:109], v[4:5], off offset:3072
	global_load_dwordx2 v[62:63], v[4:5], off offset:3584
	v_ashrrev_i32_e32 v6, 11, v12
	v_mul_hi_i32_i24_e32 v7, 0xc000, v6
	v_mul_i32_i24_e32 v6, 0xc000, v6
	v_lshl_add_u64 v[6:7], s[8:9], 0, v[6:7]
	v_lshl_add_u64 v[76:77], v[6:7], 0, s[12:13]
	v_lshl_add_u64 v[60:61], v[6:7], 0, s[14:15]
	v_lshl_add_u64 v[46:47], v[76:77], 0, v[30:31]
	v_lshl_add_u64 v[48:49], v[60:61], 0, v[30:31]
	global_load_dwordx4 v[4:7], v[46:47], off
	global_load_dwordx4 v[8:11], v[48:49], off
	v_lshl_add_u64 v[156:157], v[28:29], 0, v[50:51]
	s_waitcnt vmcnt(18)
	v_lshlrev_b32_e32 v52, 16, v57
	s_waitcnt vmcnt(17)
	v_lshlrev_b32_e32 v68, 16, v59
	v_and_b32_e32 v69, 0xffff0000, v59
	v_lshlrev_b32_e32 v120, 16, v58
	s_waitcnt vmcnt(14)
	v_and_b32_e32 v79, 0xffff0000, v74
	s_waitcnt vmcnt(13)
	v_and_b32_e32 v149, 0xffff0000, v80
	s_waitcnt vmcnt(12)
	v_and_b32_e32 v143, 0xffff0000, v82
	s_waitcnt vmcnt(11)
	v_and_b32_e32 v129, 0xffff0000, v84
	v_lshlrev_b32_e32 v78, 16, v74
	v_lshlrev_b32_e32 v148, 16, v80
	v_lshlrev_b32_e32 v140, 16, v83
	v_and_b32_e32 v141, 0xffff0000, v83
	v_lshlrev_b32_e32 v142, 16, v82
	v_lshlrev_b32_e32 v128, 16, v84
	v_mov_b32_e32 v82, v79
	v_mov_b32_e32 v83, v149
	v_mov_b32_e32 v104, v143
	v_mov_b32_e32 v105, v129
	v_and_b32_e32 v121, 0xffff0000, v58
	v_lshlrev_b32_e32 v58, 16, v75
	v_and_b32_e32 v59, 0xffff0000, v75
	v_lshlrev_b32_e32 v74, 16, v81
	v_and_b32_e32 v75, 0xffff0000, v81
	v_lshlrev_b32_e32 v124, 16, v85
	v_mov_b32_e32 v80, v78
	v_mov_b32_e32 v81, v148
	v_mov_b32_e32 v102, v142
	v_mov_b32_e32 v103, v128
	v_pk_mul_f32 v[82:83], v[82:83], v[82:83]
	v_pk_mul_f32 v[104:105], v[104:105], v[104:105]
	v_lshlrev_b32_e32 v70, 16, v65
	v_and_b32_e32 v71, 0xffff0000, v65
	v_lshlrev_b32_e32 v116, 16, v64
	v_and_b32_e32 v117, 0xffff0000, v64
	v_and_b32_e32 v125, 0xffff0000, v85
	v_mov_b32_e32 v64, v58
	v_mov_b32_e32 v65, v74
	v_mov_b32_e32 v84, v140
	v_mov_b32_e32 v85, v124
	v_pk_fma_f32 v[80:81], v[80:81], v[80:81], v[82:83]
	v_pk_fma_f32 v[82:83], v[102:103], v[102:103], v[104:105]
	s_waitcnt vmcnt(5)
	v_and_b32_e32 v107, 0xffff0000, v96
	s_waitcnt vmcnt(4)
	v_and_b32_e32 v103, 0xffff0000, v98
	v_and_b32_e32 v53, 0xffff0000, v57
	v_lshlrev_b32_e32 v54, 16, v56
	v_and_b32_e32 v55, 0xffff0000, v56
	v_lshlrev_b32_e32 v56, 16, v67
	v_and_b32_e32 v57, 0xffff0000, v67
	v_lshlrev_b32_e32 v72, 16, v66
	v_and_b32_e32 v73, 0xffff0000, v66
	v_mov_b32_e32 v66, v59
	v_mov_b32_e32 v67, v75
	v_mov_b32_e32 v100, v141
	v_mov_b32_e32 v101, v125
	v_pk_fma_f32 v[64:65], v[64:65], v[64:65], v[80:81]
	v_pk_fma_f32 v[80:81], v[84:85], v[84:85], v[82:83]
	v_lshlrev_b32_e32 v136, 16, v87
	v_and_b32_e32 v137, 0xffff0000, v87
	v_lshlrev_b32_e32 v138, 16, v86
	v_and_b32_e32 v139, 0xffff0000, v86
	v_lshlrev_b32_e32 v106, 16, v96
	v_lshlrev_b32_e32 v102, 16, v98
	v_mov_b32_e32 v86, v107
	v_mov_b32_e32 v87, v103
	v_pk_fma_f32 v[64:65], v[66:67], v[66:67], v[64:65]
	v_pk_fma_f32 v[66:67], v[100:101], v[100:101], v[80:81]
	v_lshlrev_b32_e32 v104, 16, v97
	v_lshlrev_b32_e32 v100, 16, v99
	v_mov_b32_e32 v84, v106
	v_mov_b32_e32 v85, v102
	v_pk_mul_f32 v[86:87], v[86:87], v[86:87]
	v_lshlrev_b32_e32 v132, 16, v89
	v_and_b32_e32 v133, 0xffff0000, v89
	v_lshlrev_b32_e32 v134, 16, v88
	v_and_b32_e32 v135, 0xffff0000, v88
	v_and_b32_e32 v105, 0xffff0000, v97
	v_and_b32_e32 v101, 0xffff0000, v99
	v_mov_b32_e32 v80, v104
	v_mov_b32_e32 v81, v100
	v_pk_fma_f32 v[84:85], v[84:85], v[84:85], v[86:87]
	v_mov_b32_e32 v88, v139
	v_mov_b32_e32 v89, v55
	v_mov_b32_e32 v82, v105
	v_mov_b32_e32 v83, v101
	v_pk_fma_f32 v[80:81], v[80:81], v[80:81], v[84:85]
	v_mov_b32_e32 v86, v138
	v_mov_b32_e32 v87, v54
	v_pk_mul_f32 v[88:89], v[88:89], v[88:89]
	v_lshlrev_b32_e32 v122, 16, v93
	v_and_b32_e32 v123, 0xffff0000, v93
	v_lshlrev_b32_e32 v126, 16, v92
	v_and_b32_e32 v127, 0xffff0000, v92
	v_pk_fma_f32 v[80:81], v[82:83], v[82:83], v[80:81]
	v_mov_b32_e32 v82, v136
	v_mov_b32_e32 v83, v52
	v_pk_fma_f32 v[86:87], v[86:87], v[86:87], v[88:89]
	v_mov_b32_e32 v92, v135
	v_mov_b32_e32 v93, v121
	v_mov_b32_e32 v84, v137
	v_mov_b32_e32 v85, v53
	v_pk_fma_f32 v[82:83], v[82:83], v[82:83], v[86:87]
	v_mov_b32_e32 v88, v134
	v_mov_b32_e32 v89, v120
	v_pk_mul_f32 v[92:93], v[92:93], v[92:93]
	v_pk_fma_f32 v[82:83], v[84:85], v[84:85], v[82:83]
	v_mov_b32_e32 v84, v132
	v_mov_b32_e32 v85, v68
	v_pk_fma_f32 v[88:89], v[88:89], v[88:89], v[92:93]
	v_mov_b32_e32 v86, v133
	v_mov_b32_e32 v87, v69
	v_pk_fma_f32 v[84:85], v[84:85], v[84:85], v[88:89]
	v_mov_b32_e32 v92, v127
	v_mov_b32_e32 v93, v117
	v_pk_fma_f32 v[84:85], v[86:87], v[86:87], v[84:85]
	v_mov_b32_e32 v88, v126
	v_mov_b32_e32 v89, v116
	v_pk_mul_f32 v[92:93], v[92:93], v[92:93]
	v_and_b32_e32 v115, 0xffff0000, v94
	v_pk_add_f32 v[82:83], v[82:83], v[84:85]
	v_mov_b32_e32 v84, v122
	v_mov_b32_e32 v85, v70
	v_pk_fma_f32 v[88:89], v[88:89], v[88:89], v[92:93]
	v_lshlrev_b32_e32 v114, 16, v94
	v_mov_b32_e32 v86, v123
	v_mov_b32_e32 v87, v71
	v_pk_fma_f32 v[84:85], v[84:85], v[84:85], v[88:89]
	v_mov_b32_e32 v92, v115
	v_mov_b32_e32 v93, v73
	v_lshlrev_b32_e32 v110, 16, v95
	v_pk_fma_f32 v[84:85], v[86:87], v[86:87], v[84:85]
	v_mov_b32_e32 v88, v114
	v_mov_b32_e32 v89, v72
	v_pk_mul_f32 v[92:93], v[92:93], v[92:93]
	v_and_b32_e32 v111, 0xffff0000, v95
	v_pk_add_f32 v[82:83], v[82:83], v[84:85]
	v_mov_b32_e32 v84, v110
	v_mov_b32_e32 v85, v56
	v_pk_fma_f32 v[88:89], v[88:89], v[88:89], v[92:93]
	v_mov_b32_e32 v86, v111
	v_mov_b32_e32 v87, v57
	v_pk_fma_f32 v[84:85], v[84:85], v[84:85], v[88:89]
	s_waitcnt vmcnt(3)
	v_and_b32_e32 v89, 0xffff0000, v108
	v_pk_fma_f32 v[84:85], v[86:87], v[86:87], v[84:85]
	v_lshlrev_b32_e32 v88, 16, v108
	v_pk_add_f32 v[82:83], v[82:83], v[84:85]
	v_mov_b32_e32 v84, v80
	v_mov_b32_e32 v85, v64
	v_pk_add_f32 v[92:93], v[82:83], v[84:85]
	s_waitcnt vmcnt(2)
	v_and_b32_e32 v85, 0xffff0000, v62
	v_lshlrev_b32_e32 v84, 16, v62
	v_mov_b32_e32 v98, v89
	v_mov_b32_e32 v99, v85
	v_lshlrev_b32_e32 v86, 16, v109
	v_lshlrev_b32_e32 v82, 16, v63
	v_mov_b32_e32 v96, v88
	v_mov_b32_e32 v97, v84
	v_pk_mul_f32 v[98:99], v[98:99], v[98:99]
	v_and_b32_e32 v87, 0xffff0000, v109
	v_and_b32_e32 v83, 0xffff0000, v63
	v_mov_b32_e32 v62, v86
	v_mov_b32_e32 v63, v82
	v_pk_fma_f32 v[96:97], v[96:97], v[96:97], v[98:99]
	v_mov_b32_e32 v94, v87
	v_mov_b32_e32 v95, v83
	v_pk_fma_f32 v[62:63], v[62:63], v[62:63], v[96:97]
	v_mov_b32_e32 v64, v81
	v_pk_fma_f32 v[62:63], v[94:95], v[94:95], v[62:63]
	v_pk_add_f32 v[64:65], v[92:93], v[64:65]
	v_mov_b32_e32 v80, v62
	v_mov_b32_e32 v81, v66
	v_pk_add_f32 v[64:65], v[64:65], v[80:81]
	v_mov_b32_e32 v66, v63
	v_pk_add_f32 v[62:63], v[64:65], v[66:67]
	ds_bpermute_b32 v65, v176, v63
	ds_bpermute_b32 v64, v176, v62
	v_add_u32_e32 v66, 2, v12
	v_ashrrev_i32_e32 v67, 31, v66
	v_lshlrev_b64 v[80:81], 12, v[66:67]
	s_waitcnt vmcnt(0)
	v_pk_add_f32 v[8:9], v[8:9], 1.0 op_sel_hi:[1,0]
	s_waitcnt lgkmcnt(0)
	v_pk_add_f32 v[62:63], v[62:63], v[64:65]
	ds_bpermute_b32 v65, v177, v63
	ds_bpermute_b32 v64, v177, v62
	v_pk_add_f32 v[10:11], v[10:11], 1.0 op_sel_hi:[1,0]
	v_lshl_add_u64 v[146:147], v[26:27], 0, v[80:81]
	global_load_dwordx2 v[130:131], v[146:147], off
	global_load_dwordx2 v[118:119], v[146:147], off offset:512
	global_load_dwordx2 v[112:113], v[146:147], off offset:1024
	global_load_dwordx2 v[108:109], v[146:147], off offset:1536
	v_lshl_add_u64 v[80:81], v[28:29], 0, v[80:81]
	s_waitcnt lgkmcnt(0)
	v_pk_add_f32 v[62:63], v[62:63], v[64:65]
	ds_bpermute_b32 v65, v178, v63
	ds_bpermute_b32 v64, v178, v62
	s_waitcnt lgkmcnt(0)
	v_pk_add_f32 v[62:63], v[62:63], v[64:65]
	ds_bpermute_b32 v65, v179, v63
	ds_bpermute_b32 v64, v179, v62
	s_waitcnt lgkmcnt(0)
	v_pk_add_f32 v[62:63], v[62:63], v[64:65]
	ds_bpermute_b32 v67, v180, v63
	ds_bpermute_b32 v66, v180, v62
	v_add_u32_e32 v64, 3, v12
	v_ashrrev_i32_e32 v65, 31, v64
	v_lshlrev_b64 v[64:65], 12, v[64:65]
	v_lshl_add_u64 v[152:153], v[26:27], 0, v[64:65]
	s_waitcnt lgkmcnt(0)
	v_pk_add_f32 v[62:63], v[62:63], v[66:67]
	ds_bpermute_b32 v67, v181, v63
	ds_bpermute_b32 v66, v181, v62
	global_load_dwordx2 v[98:99], v[152:153], off
	global_load_dwordx2 v[96:97], v[152:153], off offset:512
	global_load_dwordx2 v[94:95], v[152:153], off offset:1024
	global_load_dwordx2 v[92:93], v[152:153], off offset:1536
	v_add_u32_e32 v12, 32, v12
	s_waitcnt lgkmcnt(0)
	v_pk_add_f32 v[62:63], v[62:63], v[66:67]
	s_nop 0
	v_pk_fma_f32 v[154:155], v[62:63], s[16:17], v[44:45] op_sel_hi:[1,0,0]
	v_lshl_add_u64 v[62:63], v[76:77], 0, v[32:33]
	v_mul_f32_e32 v13, 0x4b800000, v155
	v_cmp_gt_f32_e32 vcc, s17, v155
	v_lshl_add_u64 v[66:67], v[60:61], 0, v[32:33]
	s_waitcnt vmcnt(7)
	v_and_b32_e32 v167, 0xffff0000, v130
	v_cndmask_b32_e32 v13, v155, v13, vcc
	v_rsq_f32_e32 v13, v13
	s_waitcnt vmcnt(6)
	v_lshlrev_b32_e32 v160, 16, v119
	v_and_b32_e32 v161, 0xffff0000, v119
	v_and_b32_e32 v165, 0xffff0000, v118
	v_mul_f32_e32 v50, 0x45800000, v13
	v_cndmask_b32_e32 v158, v13, v50, vcc
	v_pk_mul_f32 v[50:51], v[158:159], v[54:55] op_sel_hi:[0,1]
	v_pk_mul_f32 v[0:1], v[0:1], v[50:51]
	v_pk_mul_f32 v[50:51], v[158:159], v[120:121] op_sel_hi:[0,1]
	v_pk_fma_f32 v[0:1], v[8:9], v[0:1], v[4:5]
	v_pk_mul_f32 v[4:5], v[158:159], v[52:53] op_sel_hi:[0,1]
	v_pk_mul_f32 v[2:3], v[2:3], v[4:5]
	v_cvt_pk_bf16_f32 v226, v0, v1
	v_pk_fma_f32 v[2:3], v[10:11], v[2:3], v[6:7]
	v_lshl_add_u64 v[54:55], v[60:61], 0, v[34:35]
	v_cvt_pk_bf16_f32 v227, v2, v3
	global_load_dwordx4 v[0:3], v[16:17], off offset:1024
	s_nop 0
	global_load_dwordx4 v[4:7], v[66:67], off
	global_load_dwordx4 v[8:11], v[62:63], off
	global_store_dwordx2 v[156:157], v[226:227], off
	v_pk_mul_f32 v[70:71], v[158:159], v[70:71] op_sel_hi:[0,1]
	v_lshl_add_u64 v[52:53], v[60:61], 0, v[36:37]
	v_pk_mul_f32 v[72:73], v[158:159], v[72:73] op_sel_hi:[0,1]
	v_pk_mul_f32 v[56:57], v[158:159], v[56:57] op_sel_hi:[0,1]
	v_pk_mul_f32 v[78:79], v[158:159], v[78:79] op_sel_hi:[0,1]
	v_pk_mul_f32 v[58:59], v[158:159], v[58:59] op_sel_hi:[0,1]
	v_pk_mul_f32 v[148:149], v[158:159], v[148:149] op_sel_hi:[0,1]
	v_pk_mul_f32 v[74:75], v[158:159], v[74:75] op_sel_hi:[0,1]
	v_pk_mul_f32 v[142:143], v[158:159], v[142:143] op_sel_hi:[0,1]
	v_pk_mul_f32 v[140:141], v[158:159], v[140:141] op_sel_hi:[0,1]
	v_pk_mul_f32 v[128:129], v[158:159], v[128:129] op_sel_hi:[0,1]
	v_pk_mul_f32 v[124:125], v[158:159], v[124:125] op_sel_hi:[0,1]
	v_mul_f32_e32 v13, 0x4b800000, v154
	v_cmp_gt_f32_e32 vcc, s17, v154
	s_waitcnt vmcnt(6)
	v_and_b32_e32 v119, 0xffff0000, v96
	v_lshlrev_b32_e32 v166, 16, v130
	v_cndmask_b32_e32 v13, v154, v13, vcc
	v_rsq_f32_e32 v13, v13
	v_lshlrev_b32_e32 v164, 16, v118
	v_lshlrev_b32_e32 v118, 16, v96
	v_mov_b32_e32 v193, v167
	v_mov_b32_e32 v200, v119
	v_mov_b32_e32 v201, v165
	v_lshlrev_b32_e32 v162, 16, v131
	v_and_b32_e32 v155, 0xffff0000, v108
	v_mov_b32_e32 v191, v166
	v_mov_b32_e32 v198, v118
	v_mov_b32_e32 v199, v164
	v_pk_mul_f32 v[200:201], v[200:201], v[200:201]
	v_and_b32_e32 v163, 0xffff0000, v131
	v_lshlrev_b32_e32 v154, 16, v108
	v_mov_b32_e32 v187, v162
	v_mov_b32_e32 v195, v160
	v_mov_b32_e32 v217, v155
	v_mov_b32_e32 v189, v163
	v_mov_b32_e32 v197, v161
	v_mov_b32_e32 v215, v154
	s_waitcnt vmcnt(3)
	v_pk_mul_f32 v[0:1], v[0:1], v[50:51]
	s_waitcnt vmcnt(2)
	v_pk_add_f32 v[4:5], v[4:5], 1.0 op_sel_hi:[1,0]
	v_pk_mul_f32 v[50:51], v[158:159], v[116:117] op_sel_hi:[0,1]
	s_waitcnt vmcnt(1)
	v_pk_fma_f32 v[0:1], v[4:5], v[0:1], v[8:9]
	v_pk_mul_f32 v[4:5], v[158:159], v[68:69] op_sel_hi:[0,1]
	v_pk_mul_f32 v[2:3], v[2:3], v[4:5]
	v_pk_add_f32 v[4:5], v[6:7], 1.0 op_sel_hi:[1,0]
	v_cvt_pk_bf16_f32 v226, v0, v1
	v_pk_fma_f32 v[2:3], v[4:5], v[2:3], v[10:11]
	v_lshl_add_u64 v[68:69], v[76:77], 0, v[34:35]
	v_cvt_pk_bf16_f32 v227, v2, v3
	global_load_dwordx4 v[0:3], v[16:17], off offset:2048
	s_nop 0
	global_load_dwordx4 v[4:7], v[54:55], off
	global_load_dwordx4 v[8:11], v[68:69], off
	global_store_dwordx2 v[156:157], v[226:227], off offset:512
	v_and_b32_e32 v159, 0xffff0000, v112
	v_lshlrev_b32_e32 v158, 16, v112
	v_lshlrev_b32_e32 v112, 16, v94
	v_mov_b32_e32 v209, v159
	v_mov_b32_e32 v206, v112
	v_mov_b32_e32 v207, v158
	s_waitcnt vmcnt(3)
	v_pk_mul_f32 v[0:1], v[0:1], v[50:51]
	s_waitcnt vmcnt(2)
	v_pk_add_f32 v[4:5], v[4:5], 1.0 op_sel_hi:[1,0]
	v_pk_mul_f32 v[2:3], v[2:3], v[70:71]
	v_pk_add_f32 v[6:7], v[6:7], 1.0 op_sel_hi:[1,0]
	s_waitcnt vmcnt(1)
	v_pk_fma_f32 v[0:1], v[0:1], v[4:5], v[8:9]
	v_pk_fma_f32 v[2:3], v[2:3], v[6:7], v[10:11]
	v_cvt_pk_bf16_f32 v226, v0, v1
	v_cvt_pk_bf16_f32 v227, v2, v3
	global_load_dwordx4 v[0:3], v[16:17], off offset:3072
	s_nop 0
	global_load_dwordx4 v[4:7], v[52:53], off
	v_lshl_add_u64 v[70:71], v[76:77], 0, v[36:37]
	global_load_dwordx4 v[8:11], v[70:71], off
	global_store_dwordx2 v[156:157], v[226:227], off offset:1024
	v_lshl_add_u64 v[50:51], v[60:61], 0, v[14:15]
	s_waitcnt vmcnt(3)
	v_pk_mul_f32 v[0:1], v[72:73], v[0:1]
	s_waitcnt vmcnt(2)
	v_pk_add_f32 v[4:5], v[4:5], 1.0 op_sel_hi:[1,0]
	v_pk_mul_f32 v[2:3], v[56:57], v[2:3]
	v_pk_add_f32 v[6:7], v[6:7], 1.0 op_sel_hi:[1,0]
	s_waitcnt vmcnt(1)
	v_pk_fma_f32 v[0:1], v[0:1], v[4:5], v[8:9]
	v_pk_fma_f32 v[2:3], v[2:3], v[6:7], v[10:11]
	v_cvt_pk_bf16_f32 v226, v0, v1
	v_cvt_pk_bf16_f32 v227, v2, v3
	global_load_dwordx4 v[0:3], v[18:19], off
	s_nop 0
	global_load_dwordx4 v[4:7], v[50:51], off
	v_lshl_add_u64 v[72:73], v[76:77], 0, v[14:15]
	global_load_dwordx4 v[8:11], v[72:73], off
	global_load_dwordx2 v[174:175], v[146:147], off offset:2048
	global_load_dwordx2 v[172:173], v[146:147], off offset:2560
	global_load_dwordx2 v[170:171], v[146:147], off offset:3072
	global_load_dwordx2 v[168:169], v[146:147], off offset:3584
	global_load_dwordx2 v[150:151], v[152:153], off offset:2048
	s_nop 0
	global_load_dwordx2 v[146:147], v[152:153], off offset:2560
	global_load_dwordx2 v[120:121], v[152:153], off offset:3072
	global_load_dwordx2 v[116:117], v[152:153], off offset:3584
	global_store_dwordx2 v[156:157], v[226:227], off offset:1536
	v_lshl_add_u64 v[56:57], v[60:61], 0, v[38:39]
	v_lshlrev_b32_e32 v152, 16, v109
	v_and_b32_e32 v153, 0xffff0000, v109
	v_mov_b32_e32 v211, v152
	v_mov_b32_e32 v213, v153
	s_waitcnt vmcnt(5)
	v_lshlrev_b32_e32 v130, 16, v169
	v_pk_mul_f32 v[0:1], v[78:79], v[0:1]
	v_pk_add_f32 v[4:5], v[4:5], 1.0 op_sel_hi:[1,0]
	v_pk_mul_f32 v[2:3], v[58:59], v[2:3]
	v_pk_add_f32 v[6:7], v[6:7], 1.0 op_sel_hi:[1,0]
	v_pk_fma_f32 v[0:1], v[0:1], v[4:5], v[8:9]
	v_pk_fma_f32 v[2:3], v[2:3], v[6:7], v[10:11]
	v_cvt_pk_bf16_f32 v226, v0, v1
	v_cvt_pk_bf16_f32 v227, v2, v3
	global_load_dwordx4 v[0:3], v[20:21], off
	s_nop 0
	global_load_dwordx4 v[4:7], v[56:57], off
	v_lshl_add_u64 v[78:79], v[76:77], 0, v[38:39]
	global_load_dwordx4 v[8:11], v[78:79], off
	global_store_dwordx2 v[156:157], v[226:227], off offset:2048
	v_lshl_add_u64 v[58:59], v[60:61], 0, v[40:41]
	v_lshl_add_u64 v[60:61], v[60:61], 0, v[42:43]
	v_and_b32_e32 v131, 0xffff0000, v169
	s_waitcnt vmcnt(5)
	v_lshlrev_b32_e32 v96, 16, v116
	v_mov_b32_e32 v169, v130
	v_lshlrev_b32_e32 v108, 16, v120
	v_and_b32_e32 v109, 0xffff0000, v120
	v_mov_b32_e32 v224, v109
	v_mov_b32_e32 v222, v108
	v_mov_b32_e32 v223, v96
	s_waitcnt vmcnt(3)
	v_pk_mul_f32 v[0:1], v[148:149], v[0:1]
	s_waitcnt vmcnt(2)
	v_pk_add_f32 v[4:5], v[4:5], 1.0 op_sel_hi:[1,0]
	v_pk_mul_f32 v[2:3], v[74:75], v[2:3]
	v_pk_add_f32 v[6:7], v[6:7], 1.0 op_sel_hi:[1,0]
	s_waitcnt vmcnt(1)
	v_pk_fma_f32 v[0:1], v[0:1], v[4:5], v[8:9]
	v_pk_fma_f32 v[2:3], v[2:3], v[6:7], v[10:11]
	v_cvt_pk_bf16_f32 v226, v0, v1
	v_cvt_pk_bf16_f32 v227, v2, v3
	global_load_dwordx4 v[0:3], v[22:23], off
	s_nop 0
	global_load_dwordx4 v[4:7], v[58:59], off
	v_lshl_add_u64 v[74:75], v[76:77], 0, v[40:41]
	global_load_dwordx4 v[8:11], v[74:75], off
	global_store_dwordx2 v[156:157], v[226:227], off offset:2560
	v_lshl_add_u64 v[76:77], v[76:77], 0, v[42:43]
	v_and_b32_e32 v149, 0xffff0000, v174
	v_lshlrev_b32_e32 v148, 16, v174
	s_waitcnt vmcnt(3)
	v_pk_mul_f32 v[0:1], v[142:143], v[0:1]
	s_waitcnt vmcnt(2)
	v_pk_add_f32 v[4:5], v[4:5], 1.0 op_sel_hi:[1,0]
	v_pk_mul_f32 v[2:3], v[140:141], v[2:3]
	v_pk_add_f32 v[6:7], v[6:7], 1.0 op_sel_hi:[1,0]
	s_waitcnt vmcnt(1)
	v_pk_fma_f32 v[0:1], v[0:1], v[4:5], v[8:9]
	v_pk_fma_f32 v[2:3], v[2:3], v[6:7], v[10:11]
	v_cvt_pk_bf16_f32 v226, v0, v1
	v_cvt_pk_bf16_f32 v227, v2, v3
	global_load_dwordx4 v[0:3], v[24:25], off
	s_nop 0
	global_load_dwordx4 v[4:7], v[60:61], off
	global_load_dwordx4 v[8:11], v[76:77], off
	global_store_dwordx2 v[156:157], v[226:227], off offset:3072
	v_and_b32_e32 v141, 0xffff0000, v172
	v_lshlrev_b32_e32 v140, 16, v172
	v_lshlrev_b32_e32 v142, 16, v175
	v_and_b32_e32 v143, 0xffff0000, v175
	v_mov_b32_e32 v120, v143
	s_waitcnt vmcnt(3)
	v_pk_mul_f32 v[0:1], v[128:129], v[0:1]
	s_waitcnt vmcnt(2)
	v_pk_add_f32 v[4:5], v[4:5], 1.0 op_sel_hi:[1,0]
	v_pk_mul_f32 v[2:3], v[124:125], v[2:3]
	v_pk_add_f32 v[6:7], v[6:7], 1.0 op_sel_hi:[1,0]
	s_waitcnt vmcnt(1)
	v_pk_fma_f32 v[0:1], v[0:1], v[4:5], v[8:9]
	v_pk_fma_f32 v[2:3], v[2:3], v[6:7], v[10:11]
	v_cvt_pk_bf16_f32 v226, v0, v1
	v_cvt_pk_bf16_f32 v227, v2, v3
	global_load_dwordx4 v[0:3], v[48:49], off
	s_nop 0
	global_load_dwordx4 v[4:7], v[16:17], off
	global_load_dwordx4 v[8:11], v[46:47], off
	global_store_dwordx2 v[156:157], v[226:227], off offset:3584
	v_lshl_add_u64 v[124:125], v[28:29], 0, v[90:91]
	v_mul_f32_e32 v90, 0x45800000, v13
	v_cndmask_b32_e32 v128, v13, v90, vcc
	v_pk_mul_f32 v[90:91], v[128:129], v[138:139] op_sel_hi:[0,1]
	v_pk_mul_f32 v[136:137], v[128:129], v[136:137] op_sel_hi:[0,1]
	v_pk_mul_f32 v[132:133], v[128:129], v[132:133] op_sel_hi:[0,1]
	v_pk_mul_f32 v[122:123], v[128:129], v[122:123] op_sel_hi:[0,1]
	v_pk_mul_f32 v[110:111], v[128:129], v[110:111] op_sel_hi:[0,1]
	v_pk_mul_f32 v[104:105], v[128:129], v[104:105] op_sel_hi:[0,1]
	v_pk_mul_f32 v[100:101], v[128:129], v[100:101] op_sel_hi:[0,1]
	v_pk_mul_f32 v[88:89], v[128:129], v[88:89] op_sel_hi:[0,1]
	v_pk_mul_f32 v[86:87], v[128:129], v[86:87] op_sel_hi:[0,1]
	v_pk_mul_f32 v[84:85], v[128:129], v[84:85] op_sel_hi:[0,1]
	v_pk_mul_f32 v[82:83], v[128:129], v[82:83] op_sel_hi:[0,1]
	v_and_b32_e32 v139, 0xffff0000, v170
	v_lshlrev_b32_e32 v156, 16, v113
	v_and_b32_e32 v157, 0xffff0000, v113
	v_lshlrev_b32_e32 v138, 16, v170
	v_and_b32_e32 v113, 0xffff0000, v94
	v_mov_b32_e32 v170, v139
	v_mov_b32_e32 v208, v113
	v_lshlrev_b32_e32 v94, 16, v117
	v_pk_mul_f32 v[208:209], v[208:209], v[208:209]
	v_mov_b32_e32 v203, v156
	v_mov_b32_e32 v205, v157
	v_mov_b32_e32 v219, v94
	s_waitcnt vmcnt(3)
	v_pk_add_f32 v[0:1], v[0:1], 1.0 op_sel_hi:[1,0]
	v_pk_add_f32 v[2:3], v[2:3], 1.0 op_sel_hi:[1,0]
	s_waitcnt vmcnt(2)
	v_pk_mul_f32 v[4:5], v[4:5], v[90:91]
	v_pk_mul_f32 v[6:7], v[6:7], v[136:137]
	s_waitcnt vmcnt(1)
	v_pk_fma_f32 v[0:1], v[0:1], v[4:5], v[8:9]
	v_pk_fma_f32 v[2:3], v[2:3], v[6:7], v[10:11]
	v_cvt_pk_bf16_f32 v226, v0, v1
	v_cvt_pk_bf16_f32 v227, v2, v3
	global_load_dwordx4 v[0:3], v[16:17], off offset:1024
	s_nop 0
	global_load_dwordx4 v[4:7], v[66:67], off
	global_load_dwordx4 v[8:11], v[62:63], off
	global_store_dwordx2 v[124:125], v[226:227], off
	v_pk_mul_f32 v[90:91], v[128:129], v[134:135] op_sel_hi:[0,1]
	v_lshlrev_b32_e32 v134, 16, v171
	v_and_b32_e32 v135, 0xffff0000, v171
	v_lshlrev_b32_e32 v136, 16, v173
	v_and_b32_e32 v137, 0xffff0000, v173
	s_waitcnt vmcnt(3)
	v_pk_mul_f32 v[0:1], v[0:1], v[90:91]
	s_waitcnt vmcnt(2)
	v_pk_add_f32 v[4:5], v[4:5], 1.0 op_sel_hi:[1,0]
	v_pk_mul_f32 v[2:3], v[2:3], v[132:133]
	v_pk_add_f32 v[6:7], v[6:7], 1.0 op_sel_hi:[1,0]
	s_waitcnt vmcnt(1)
	v_pk_fma_f32 v[0:1], v[4:5], v[0:1], v[8:9]
	v_pk_fma_f32 v[2:3], v[6:7], v[2:3], v[10:11]
	v_cvt_pk_bf16_f32 v226, v0, v1
	v_cvt_pk_bf16_f32 v227, v2, v3
	global_load_dwordx4 v[0:3], v[16:17], off offset:2048
	s_nop 0
	global_load_dwordx4 v[4:7], v[54:55], off
	global_load_dwordx4 v[8:11], v[68:69], off
	global_store_dwordx2 v[124:125], v[226:227], off offset:512
	v_pk_mul_f32 v[90:91], v[128:129], v[126:127] op_sel_hi:[0,1]
	v_and_b32_e32 v133, 0xffff0000, v168
	v_and_b32_e32 v127, 0xffff0000, v98
	v_lshlrev_b32_e32 v132, 16, v168
	v_lshlrev_b32_e32 v126, 16, v98
	v_lshlrev_b32_e32 v98, 16, v151
	v_mov_b32_e32 v171, v133
	v_mov_b32_e32 v192, v127
	v_mov_b32_e32 v190, v126
	v_pk_mul_f32 v[170:171], v[170:171], v[170:171]
	v_pk_mul_f32 v[192:193], v[192:193], v[192:193]
	v_mov_b32_e32 v168, v134
	v_mov_b32_e32 v172, v98
	s_waitcnt vmcnt(3)
	v_pk_mul_f32 v[0:1], v[0:1], v[90:91]
	s_waitcnt vmcnt(2)
	v_pk_add_f32 v[4:5], v[4:5], 1.0 op_sel_hi:[1,0]
	v_pk_mul_f32 v[2:3], v[2:3], v[122:123]
	v_pk_add_f32 v[6:7], v[6:7], 1.0 op_sel_hi:[1,0]
	s_waitcnt vmcnt(1)
	v_pk_fma_f32 v[0:1], v[0:1], v[4:5], v[8:9]
	v_pk_fma_f32 v[2:3], v[2:3], v[6:7], v[10:11]
	v_cvt_pk_bf16_f32 v226, v0, v1
	v_cvt_pk_bf16_f32 v227, v2, v3
	global_load_dwordx4 v[0:3], v[16:17], off offset:3072
	s_nop 0
	global_load_dwordx4 v[4:7], v[52:53], off
	global_load_dwordx4 v[8:11], v[70:71], off
	global_store_dwordx2 v[124:125], v[226:227], off offset:1024
	v_pk_mul_f32 v[90:91], v[128:129], v[114:115] op_sel_hi:[0,1]
	v_lshlrev_b32_e32 v122, 16, v99
	v_and_b32_e32 v123, 0xffff0000, v99
	v_and_b32_e32 v99, 0xffff0000, v151
	v_mov_b32_e32 v151, v141
	v_lshlrev_b32_e32 v114, 16, v97
	v_and_b32_e32 v115, 0xffff0000, v97
	v_and_b32_e32 v97, 0xffff0000, v116
	v_mov_b32_e32 v116, v142
	v_mov_b32_e32 v186, v122
	v_mov_b32_e32 v194, v114
	v_mov_b32_e32 v188, v123
	v_mov_b32_e32 v196, v115
	v_mov_b32_e32 v225, v97
	v_mov_b32_e32 v174, v99
	v_pk_mul_f32 v[224:225], v[224:225], v[224:225]
	s_waitcnt vmcnt(3)
	v_pk_mul_f32 v[0:1], v[90:91], v[0:1]
	s_waitcnt vmcnt(2)
	v_pk_add_f32 v[4:5], v[4:5], 1.0 op_sel_hi:[1,0]
	v_pk_mul_f32 v[2:3], v[110:111], v[2:3]
	v_pk_add_f32 v[6:7], v[6:7], 1.0 op_sel_hi:[1,0]
	s_waitcnt vmcnt(1)
	v_pk_fma_f32 v[0:1], v[0:1], v[4:5], v[8:9]
	v_pk_fma_f32 v[2:3], v[2:3], v[6:7], v[10:11]
	v_cvt_pk_bf16_f32 v226, v0, v1
	v_cvt_pk_bf16_f32 v227, v2, v3
	global_load_dwordx4 v[0:3], v[18:19], off
	s_nop 0
	global_load_dwordx4 v[4:7], v[50:51], off
	global_load_dwordx4 v[8:11], v[72:73], off
	global_store_dwordx2 v[124:125], v[226:227], off offset:1536
	v_pk_mul_f32 v[90:91], v[128:129], v[106:107] op_sel_hi:[0,1]
	v_lshlrev_b32_e32 v106, 16, v92
	v_and_b32_e32 v107, 0xffff0000, v92
	v_lshlrev_b32_e32 v92, 16, v146
	v_mov_b32_e32 v183, v92
	v_lshlrev_b32_e32 v110, 16, v95
	v_and_b32_e32 v111, 0xffff0000, v95
	v_and_b32_e32 v95, 0xffff0000, v117
	v_mov_b32_e32 v117, v136
	v_mov_b32_e32 v216, v107
	v_mov_b32_e32 v202, v110
	v_mov_b32_e32 v214, v106
	v_pk_mul_f32 v[216:217], v[216:217], v[216:217]
	v_mov_b32_e32 v204, v111
	v_mov_b32_e32 v221, v95
	s_waitcnt vmcnt(3)
	v_pk_mul_f32 v[0:1], v[90:91], v[0:1]
	s_waitcnt vmcnt(2)
	v_pk_add_f32 v[4:5], v[4:5], 1.0 op_sel_hi:[1,0]
	v_pk_mul_f32 v[2:3], v[104:105], v[2:3]
	v_pk_add_f32 v[6:7], v[6:7], 1.0 op_sel_hi:[1,0]
	s_waitcnt vmcnt(1)
	v_pk_fma_f32 v[0:1], v[0:1], v[4:5], v[8:9]
	v_pk_fma_f32 v[2:3], v[2:3], v[6:7], v[10:11]
	v_cvt_pk_bf16_f32 v226, v0, v1
	v_cvt_pk_bf16_f32 v227, v2, v3
	global_load_dwordx4 v[0:3], v[20:21], off
	s_nop 0
	global_load_dwordx4 v[4:7], v[56:57], off
	global_load_dwordx4 v[8:11], v[78:79], off
	global_store_dwordx2 v[124:125], v[226:227], off offset:2048
	v_pk_mul_f32 v[90:91], v[128:129], v[102:103] op_sel_hi:[0,1]
	v_lshlrev_b32_e32 v102, 16, v93
	v_and_b32_e32 v103, 0xffff0000, v93
	v_and_b32_e32 v93, 0xffff0000, v146
	v_mov_b32_e32 v185, v93
	v_mov_b32_e32 v146, v148
	v_lshlrev_b32_e32 v104, 16, v121
	v_and_b32_e32 v105, 0xffff0000, v121
	v_mov_b32_e32 v121, v137
	v_mov_b32_e32 v210, v102
	v_mov_b32_e32 v212, v103
	v_mov_b32_e32 v218, v104
	v_mov_b32_e32 v220, v105
	s_waitcnt vmcnt(3)
	v_pk_mul_f32 v[0:1], v[90:91], v[0:1]
	s_waitcnt vmcnt(2)
	v_pk_add_f32 v[4:5], v[4:5], 1.0 op_sel_hi:[1,0]
	v_pk_mul_f32 v[2:3], v[100:101], v[2:3]
	v_pk_add_f32 v[6:7], v[6:7], 1.0 op_sel_hi:[1,0]
	s_waitcnt vmcnt(1)
	v_pk_fma_f32 v[0:1], v[0:1], v[4:5], v[8:9]
	v_pk_fma_f32 v[2:3], v[2:3], v[6:7], v[10:11]
	v_cvt_pk_bf16_f32 v226, v0, v1
	v_cvt_pk_bf16_f32 v227, v2, v3
	global_load_dwordx4 v[0:3], v[22:23], off
	s_nop 0
	global_load_dwordx4 v[8:11], v[58:59], off
	global_load_dwordx4 v[4:7], v[74:75], off
	global_store_dwordx2 v[124:125], v[226:227], off offset:2560
	v_and_b32_e32 v101, 0xffff0000, v150
	v_lshlrev_b32_e32 v100, 16, v150
	v_mov_b32_e32 v150, v149
	v_mov_b32_e32 v184, v101
	v_lshlrev_b32_e32 v90, 16, v147
	v_and_b32_e32 v91, 0xffff0000, v147
	v_mov_b32_e32 v147, v140
	v_mov_b32_e32 v182, v100
	v_pk_mul_f32 v[150:151], v[150:151], v[150:151]
	v_pk_mul_f32 v[184:185], v[184:185], v[184:185]
	v_mov_b32_e32 v173, v90
	v_pk_fma_f32 v[146:147], v[146:147], v[146:147], v[150:151]
	v_pk_fma_f32 v[150:151], v[182:183], v[182:183], v[184:185]
	v_pk_fma_f32 v[182:183], v[198:199], v[198:199], v[200:201]
	v_pk_fma_f32 v[184:185], v[206:207], v[206:207], v[208:209]
	v_pk_fma_f32 v[116:117], v[116:117], v[116:117], v[146:147]
	v_pk_fma_f32 v[146:147], v[172:173], v[172:173], v[150:151]
	v_pk_fma_f32 v[116:117], v[120:121], v[120:121], v[116:117]
	v_mov_b32_e32 v175, v91
	s_waitcnt vmcnt(3)
	v_pk_mul_f32 v[0:1], v[88:89], v[0:1]
	s_waitcnt vmcnt(2)
	v_pk_add_f32 v[8:9], v[8:9], 1.0 op_sel_hi:[1,0]
	v_pk_mul_f32 v[2:3], v[86:87], v[2:3]
	v_pk_add_f32 v[10:11], v[10:11], 1.0 op_sel_hi:[1,0]
	s_waitcnt vmcnt(1)
	v_pk_fma_f32 v[0:1], v[0:1], v[8:9], v[4:5]
	v_pk_fma_f32 v[2:3], v[2:3], v[10:11], v[6:7]
	v_cvt_pk_bf16_f32 v226, v0, v1
	v_cvt_pk_bf16_f32 v227, v2, v3
	global_load_dwordx4 v[0:3], v[24:25], off
	s_nop 0
	global_load_dwordx4 v[4:7], v[76:77], off
	global_load_dwordx4 v[8:11], v[60:61], off
	global_store_dwordx2 v[124:125], v[226:227], off offset:3072
	v_mov_b32_e32 v88, v138
	v_mov_b32_e32 v89, v132
	v_pk_fma_f32 v[88:89], v[88:89], v[88:89], v[170:171]
	v_pk_fma_f32 v[170:171], v[190:191], v[190:191], v[192:193]
	v_pk_fma_f32 v[88:89], v[168:169], v[168:169], v[88:89]
	v_pk_fma_f32 v[150:151], v[186:187], v[186:187], v[170:171]
	v_pk_fma_f32 v[168:169], v[194:195], v[194:195], v[182:183]
	v_pk_fma_f32 v[190:191], v[214:215], v[214:215], v[216:217]
	v_pk_fma_f32 v[120:121], v[188:189], v[188:189], v[150:151]
	v_pk_fma_f32 v[128:129], v[196:197], v[196:197], v[168:169]
	v_mov_b32_e32 v86, v135
	v_mov_b32_e32 v87, v131
	v_pk_add_f32 v[120:121], v[120:121], v[128:129]
	v_pk_fma_f32 v[192:193], v[222:223], v[222:223], v[224:225]
	v_pk_fma_f32 v[86:87], v[86:87], v[86:87], v[88:89]
	v_pk_fma_f32 v[88:89], v[174:175], v[174:175], v[146:147]
	v_mov_b32_e32 v129, v116
	v_mov_b32_e32 v128, v88
	v_mov_b32_e32 v116, v89
	v_mov_b32_e32 v89, v86
	s_waitcnt vmcnt(3)
	v_pk_mul_f32 v[0:1], v[84:85], v[0:1]
	v_pk_mul_f32 v[2:3], v[82:83], v[2:3]
	s_waitcnt vmcnt(1)
	v_pk_add_f32 v[8:9], v[8:9], 1.0 op_sel_hi:[1,0]
	v_pk_add_f32 v[10:11], v[10:11], 1.0 op_sel_hi:[1,0]
	v_pk_fma_f32 v[0:1], v[0:1], v[8:9], v[4:5]
	v_pk_fma_f32 v[2:3], v[2:3], v[10:11], v[6:7]
	v_cvt_pk_bf16_f32 v226, v0, v1
	v_cvt_pk_bf16_f32 v227, v2, v3
	global_load_dwordx4 v[0:3], v[46:47], off
	s_nop 0
	global_load_dwordx4 v[4:7], v[48:49], off
	global_load_dwordx4 v[8:11], v[16:17], off
	global_store_dwordx2 v[124:125], v[226:227], off offset:3584
	v_pk_fma_f32 v[82:83], v[202:203], v[202:203], v[184:185]
	v_pk_fma_f32 v[84:85], v[210:211], v[210:211], v[190:191]
	v_pk_fma_f32 v[82:83], v[204:205], v[204:205], v[82:83]
	v_pk_fma_f32 v[84:85], v[212:213], v[212:213], v[84:85]
	v_pk_add_f32 v[82:83], v[120:121], v[82:83]
	v_pk_fma_f32 v[124:125], v[218:219], v[218:219], v[192:193]
	v_pk_add_f32 v[82:83], v[82:83], v[84:85]
	v_pk_fma_f32 v[124:125], v[220:221], v[220:221], v[124:125]
	v_pk_add_f32 v[82:83], v[82:83], v[128:129]
	v_mov_b32_e32 v88, v124
	v_pk_add_f32 v[82:83], v[82:83], v[116:117]
	v_mov_b32_e32 v86, v125
	v_pk_add_f32 v[82:83], v[82:83], v[88:89]
	s_waitcnt vmcnt(2)
	v_pk_add_f32 v[4:5], v[4:5], 1.0 op_sel_hi:[1,0]
	v_pk_add_f32 v[82:83], v[82:83], v[86:87]
	ds_bpermute_b32 v85, v176, v83
	ds_bpermute_b32 v84, v176, v82
	v_pk_add_f32 v[6:7], v[6:7], 1.0 op_sel_hi:[1,0]
	s_waitcnt lgkmcnt(0)
	v_pk_add_f32 v[82:83], v[82:83], v[84:85]
	ds_bpermute_b32 v85, v177, v83
	ds_bpermute_b32 v84, v177, v82
	s_waitcnt lgkmcnt(0)
	v_pk_add_f32 v[82:83], v[82:83], v[84:85]
	ds_bpermute_b32 v85, v178, v83
	ds_bpermute_b32 v84, v178, v82
	s_waitcnt lgkmcnt(0)
	v_pk_add_f32 v[82:83], v[82:83], v[84:85]
	ds_bpermute_b32 v85, v179, v83
	ds_bpermute_b32 v84, v179, v82
	s_waitcnt lgkmcnt(0)
	v_pk_add_f32 v[82:83], v[82:83], v[84:85]
	ds_bpermute_b32 v85, v180, v83
	ds_bpermute_b32 v84, v180, v82
	s_waitcnt lgkmcnt(0)
	v_pk_add_f32 v[82:83], v[82:83], v[84:85]
	ds_bpermute_b32 v85, v181, v83
	ds_bpermute_b32 v84, v181, v82
	s_waitcnt lgkmcnt(0)
	v_pk_add_f32 v[82:83], v[82:83], v[84:85]
	s_nop 0
	v_pk_fma_f32 v[82:83], v[82:83], s[16:17], v[44:45] op_sel_hi:[1,0,0]
	s_nop 0
	v_mul_f32_e32 v13, 0x4b800000, v83
	v_cmp_gt_f32_e32 vcc, s17, v83
	s_nop 1
	v_cndmask_b32_e32 v13, v83, v13, vcc
	v_rsq_f32_e32 v13, v13
	s_nop 0
	v_mul_f32_e32 v83, 0x45800000, v13
	v_cndmask_b32_e32 v84, v13, v83, vcc
	v_pk_mul_f32 v[86:87], v[84:85], v[166:167] op_sel_hi:[0,1]
	v_pk_mul_f32 v[88:89], v[84:85], v[162:163] op_sel_hi:[0,1]
	s_waitcnt vmcnt(1)
	v_pk_mul_f32 v[8:9], v[8:9], v[86:87]
	v_pk_mul_f32 v[10:11], v[10:11], v[88:89]
	v_pk_fma_f32 v[0:1], v[4:5], v[8:9], v[0:1]
	v_pk_fma_f32 v[2:3], v[6:7], v[10:11], v[2:3]
	v_cvt_pk_bf16_f32 v226, v0, v1
	v_cvt_pk_bf16_f32 v227, v2, v3
	global_load_dwordx4 v[0:3], v[16:17], off offset:1024
	s_nop 0
	global_load_dwordx4 v[4:7], v[66:67], off
	global_load_dwordx4 v[8:11], v[62:63], off
	global_store_dwordx2 v[80:81], v[226:227], off
	v_pk_mul_f32 v[86:87], v[84:85], v[164:165] op_sel_hi:[0,1]
	v_pk_mul_f32 v[88:89], v[84:85], v[160:161] op_sel_hi:[0,1]
	v_mul_f32_e32 v13, 0x4b800000, v82
	v_cmp_gt_f32_e32 vcc, s17, v82
	s_waitcnt vmcnt(3)
	v_pk_mul_f32 v[0:1], v[0:1], v[86:87]
	s_waitcnt vmcnt(2)
	v_pk_add_f32 v[4:5], v[4:5], 1.0 op_sel_hi:[1,0]
	v_pk_mul_f32 v[2:3], v[2:3], v[88:89]
	v_pk_add_f32 v[6:7], v[6:7], 1.0 op_sel_hi:[1,0]
	s_waitcnt vmcnt(1)
	v_pk_fma_f32 v[0:1], v[4:5], v[0:1], v[8:9]
	v_pk_fma_f32 v[2:3], v[6:7], v[2:3], v[10:11]
	v_cvt_pk_bf16_f32 v226, v0, v1
	v_cvt_pk_bf16_f32 v227, v2, v3
	global_load_dwordx4 v[0:3], v[16:17], off offset:2048
	s_nop 0
	global_load_dwordx4 v[4:7], v[54:55], off
	global_load_dwordx4 v[8:11], v[68:69], off
	global_store_dwordx2 v[80:81], v[226:227], off offset:512
	v_pk_mul_f32 v[86:87], v[84:85], v[158:159] op_sel_hi:[0,1]
	v_pk_mul_f32 v[88:89], v[84:85], v[156:157] op_sel_hi:[0,1]
	v_cndmask_b32_e32 v13, v82, v13, vcc
	v_rsq_f32_e32 v13, v13
	s_waitcnt vmcnt(3)
	v_pk_mul_f32 v[0:1], v[0:1], v[86:87]
	s_waitcnt vmcnt(2)
	v_pk_add_f32 v[4:5], v[4:5], 1.0 op_sel_hi:[1,0]
	v_pk_mul_f32 v[2:3], v[2:3], v[88:89]
	v_pk_add_f32 v[6:7], v[6:7], 1.0 op_sel_hi:[1,0]
	s_waitcnt vmcnt(1)
	v_pk_fma_f32 v[0:1], v[0:1], v[4:5], v[8:9]
	v_pk_fma_f32 v[2:3], v[2:3], v[6:7], v[10:11]
	v_cvt_pk_bf16_f32 v226, v0, v1
	v_cvt_pk_bf16_f32 v227, v2, v3
	global_load_dwordx4 v[0:3], v[16:17], off offset:3072
	s_nop 0
	global_load_dwordx4 v[4:7], v[52:53], off
	global_load_dwordx4 v[8:11], v[70:71], off
	global_store_dwordx2 v[80:81], v[226:227], off offset:1024
	v_pk_mul_f32 v[86:87], v[84:85], v[154:155] op_sel_hi:[0,1]
	v_pk_mul_f32 v[88:89], v[84:85], v[152:153] op_sel_hi:[0,1]
	s_waitcnt vmcnt(3)
	v_pk_mul_f32 v[0:1], v[86:87], v[0:1]
	s_waitcnt vmcnt(2)
	v_pk_add_f32 v[4:5], v[4:5], 1.0 op_sel_hi:[1,0]
	v_pk_mul_f32 v[2:3], v[88:89], v[2:3]
	v_pk_add_f32 v[6:7], v[6:7], 1.0 op_sel_hi:[1,0]
	s_waitcnt vmcnt(1)
	v_pk_fma_f32 v[0:1], v[0:1], v[4:5], v[8:9]
	v_pk_fma_f32 v[2:3], v[2:3], v[6:7], v[10:11]
	v_cvt_pk_bf16_f32 v226, v0, v1
	v_cvt_pk_bf16_f32 v227, v2, v3
	global_load_dwordx4 v[0:3], v[18:19], off
	s_nop 0
	global_load_dwordx4 v[4:7], v[50:51], off
	global_load_dwordx4 v[8:11], v[72:73], off
	global_store_dwordx2 v[80:81], v[226:227], off offset:1536
	v_pk_mul_f32 v[86:87], v[84:85], v[148:149] op_sel_hi:[0,1]
	v_pk_mul_f32 v[88:89], v[84:85], v[142:143] op_sel_hi:[0,1]
	s_waitcnt vmcnt(3)
	v_pk_mul_f32 v[0:1], v[86:87], v[0:1]
	s_waitcnt vmcnt(2)
	v_pk_add_f32 v[4:5], v[4:5], 1.0 op_sel_hi:[1,0]
	v_pk_mul_f32 v[2:3], v[88:89], v[2:3]
	v_pk_add_f32 v[6:7], v[6:7], 1.0 op_sel_hi:[1,0]
	s_waitcnt vmcnt(1)
	v_pk_fma_f32 v[0:1], v[0:1], v[4:5], v[8:9]
	v_pk_fma_f32 v[2:3], v[2:3], v[6:7], v[10:11]
	v_cvt_pk_bf16_f32 v226, v0, v1
	v_cvt_pk_bf16_f32 v227, v2, v3
	global_load_dwordx4 v[0:3], v[20:21], off
	s_nop 0
	global_load_dwordx4 v[4:7], v[56:57], off
	global_load_dwordx4 v[8:11], v[78:79], off
	global_store_dwordx2 v[80:81], v[226:227], off offset:2048
	v_pk_mul_f32 v[86:87], v[84:85], v[140:141] op_sel_hi:[0,1]
	v_pk_mul_f32 v[88:89], v[84:85], v[136:137] op_sel_hi:[0,1]
	s_waitcnt vmcnt(3)
	v_pk_mul_f32 v[0:1], v[86:87], v[0:1]
	s_waitcnt vmcnt(2)
	v_pk_add_f32 v[4:5], v[4:5], 1.0 op_sel_hi:[1,0]
	v_pk_mul_f32 v[2:3], v[88:89], v[2:3]
	v_pk_add_f32 v[6:7], v[6:7], 1.0 op_sel_hi:[1,0]
	s_waitcnt vmcnt(1)
	v_pk_fma_f32 v[0:1], v[0:1], v[4:5], v[8:9]
	v_pk_fma_f32 v[2:3], v[2:3], v[6:7], v[10:11]
	v_cvt_pk_bf16_f32 v226, v0, v1
	v_cvt_pk_bf16_f32 v227, v2, v3
	global_load_dwordx4 v[0:3], v[22:23], off
	s_nop 0
	global_load_dwordx4 v[4:7], v[58:59], off
	global_load_dwordx4 v[8:11], v[74:75], off
	global_store_dwordx2 v[80:81], v[226:227], off offset:2560
	v_pk_mul_f32 v[86:87], v[84:85], v[138:139] op_sel_hi:[0,1]
	v_pk_mul_f32 v[88:89], v[84:85], v[134:135] op_sel_hi:[0,1]
	s_waitcnt vmcnt(3)
	v_pk_mul_f32 v[0:1], v[86:87], v[0:1]
	s_waitcnt vmcnt(2)
	v_pk_add_f32 v[4:5], v[4:5], 1.0 op_sel_hi:[1,0]
	v_pk_mul_f32 v[2:3], v[88:89], v[2:3]
	v_pk_add_f32 v[6:7], v[6:7], 1.0 op_sel_hi:[1,0]
	s_waitcnt vmcnt(1)
	v_pk_fma_f32 v[0:1], v[0:1], v[4:5], v[8:9]
	v_pk_fma_f32 v[2:3], v[2:3], v[6:7], v[10:11]
	v_cvt_pk_bf16_f32 v226, v0, v1
	v_cvt_pk_bf16_f32 v227, v2, v3
	global_load_dwordx4 v[0:3], v[24:25], off
	s_nop 0
	global_load_dwordx4 v[4:7], v[60:61], off
	global_load_dwordx4 v[8:11], v[76:77], off
	global_store_dwordx2 v[80:81], v[226:227], off offset:3072
	v_pk_mul_f32 v[86:87], v[84:85], v[132:133] op_sel_hi:[0,1]
	v_pk_mul_f32 v[84:85], v[84:85], v[130:131] op_sel_hi:[0,1]
	s_waitcnt vmcnt(3)
	v_pk_mul_f32 v[0:1], v[86:87], v[0:1]
	s_waitcnt vmcnt(2)
	v_pk_add_f32 v[4:5], v[4:5], 1.0 op_sel_hi:[1,0]
	v_pk_mul_f32 v[2:3], v[84:85], v[2:3]
	v_pk_add_f32 v[6:7], v[6:7], 1.0 op_sel_hi:[1,0]
	s_waitcnt vmcnt(1)
	v_pk_fma_f32 v[0:1], v[0:1], v[4:5], v[8:9]
	v_pk_fma_f32 v[2:3], v[2:3], v[6:7], v[10:11]
	v_cvt_pk_bf16_f32 v226, v0, v1
	v_cvt_pk_bf16_f32 v227, v2, v3
	global_load_dwordx4 v[0:3], v[48:49], off
	s_nop 0
	global_load_dwordx4 v[4:7], v[16:17], off
	global_load_dwordx4 v[8:11], v[46:47], off
	global_store_dwordx2 v[80:81], v[226:227], off offset:3584
	v_mul_f32_e32 v48, 0x45800000, v13
	v_cndmask_b32_e32 v48, v13, v48, vcc
	v_lshl_add_u64 v[46:47], v[28:29], 0, v[64:65]
	v_pk_mul_f32 v[64:65], v[48:49], v[126:127] op_sel_hi:[0,1]
	v_pk_mul_f32 v[80:81], v[48:49], v[122:123] op_sel_hi:[0,1]
	v_and_b32_e32 v13, 32, v12
	v_cmp_eq_u32_e32 vcc, 0, v13
	s_or_b64 s[10:11], vcc, s[10:11]
	s_waitcnt vmcnt(3)
	v_pk_add_f32 v[0:1], v[0:1], 1.0 op_sel_hi:[1,0]
	v_pk_add_f32 v[2:3], v[2:3], 1.0 op_sel_hi:[1,0]
	s_waitcnt vmcnt(2)
	v_pk_mul_f32 v[4:5], v[4:5], v[64:65]
	v_pk_mul_f32 v[6:7], v[6:7], v[80:81]
	s_waitcnt vmcnt(1)
	v_pk_fma_f32 v[0:1], v[0:1], v[4:5], v[8:9]
	v_pk_fma_f32 v[2:3], v[2:3], v[6:7], v[10:11]
	v_cvt_pk_bf16_f32 v226, v0, v1
	v_cvt_pk_bf16_f32 v227, v2, v3
	global_load_dwordx4 v[0:3], v[16:17], off offset:1024
	s_nop 0
	global_load_dwordx4 v[4:7], v[66:67], off
	global_load_dwordx4 v[8:11], v[62:63], off
	global_store_dwordx2 v[46:47], v[226:227], off
	v_pk_mul_f32 v[62:63], v[48:49], v[118:119] op_sel_hi:[0,1]
	v_pk_mul_f32 v[64:65], v[48:49], v[114:115] op_sel_hi:[0,1]
	s_waitcnt vmcnt(3)
	v_pk_mul_f32 v[0:1], v[0:1], v[62:63]
	s_waitcnt vmcnt(2)
	v_pk_add_f32 v[4:5], v[4:5], 1.0 op_sel_hi:[1,0]
	v_pk_mul_f32 v[2:3], v[2:3], v[64:65]
	v_pk_add_f32 v[6:7], v[6:7], 1.0 op_sel_hi:[1,0]
	s_waitcnt vmcnt(1)
	v_pk_fma_f32 v[0:1], v[4:5], v[0:1], v[8:9]
	v_pk_fma_f32 v[2:3], v[6:7], v[2:3], v[10:11]
	v_cvt_pk_bf16_f32 v226, v0, v1
	v_cvt_pk_bf16_f32 v227, v2, v3
	global_load_dwordx4 v[0:3], v[16:17], off offset:2048
	s_nop 0
	global_load_dwordx4 v[4:7], v[54:55], off
	global_load_dwordx4 v[8:11], v[68:69], off
	global_store_dwordx2 v[46:47], v[226:227], off offset:512
	v_pk_mul_f32 v[54:55], v[48:49], v[112:113] op_sel_hi:[0,1]
	v_pk_mul_f32 v[62:63], v[48:49], v[110:111] op_sel_hi:[0,1]
	s_waitcnt vmcnt(3)
	v_pk_mul_f32 v[0:1], v[0:1], v[54:55]
	s_waitcnt vmcnt(2)
	v_pk_add_f32 v[4:5], v[4:5], 1.0 op_sel_hi:[1,0]
	v_pk_mul_f32 v[2:3], v[2:3], v[62:63]
	v_pk_add_f32 v[6:7], v[6:7], 1.0 op_sel_hi:[1,0]
	s_waitcnt vmcnt(1)
	v_pk_fma_f32 v[0:1], v[0:1], v[4:5], v[8:9]
	v_pk_fma_f32 v[2:3], v[2:3], v[6:7], v[10:11]
	v_cvt_pk_bf16_f32 v226, v0, v1
	v_cvt_pk_bf16_f32 v227, v2, v3
	global_load_dwordx4 v[0:3], v[16:17], off offset:3072
	s_nop 0
	global_load_dwordx4 v[4:7], v[52:53], off
	global_load_dwordx4 v[8:11], v[70:71], off
	global_store_dwordx2 v[46:47], v[226:227], off offset:1024
	v_pk_mul_f32 v[52:53], v[48:49], v[106:107] op_sel_hi:[0,1]
	v_pk_mul_f32 v[54:55], v[48:49], v[102:103] op_sel_hi:[0,1]
	s_waitcnt vmcnt(3)
	v_pk_mul_f32 v[0:1], v[52:53], v[0:1]
	s_waitcnt vmcnt(2)
	v_pk_add_f32 v[4:5], v[4:5], 1.0 op_sel_hi:[1,0]
	v_pk_mul_f32 v[2:3], v[54:55], v[2:3]
	v_pk_add_f32 v[6:7], v[6:7], 1.0 op_sel_hi:[1,0]
	s_waitcnt vmcnt(1)
	v_pk_fma_f32 v[0:1], v[0:1], v[4:5], v[8:9]
	v_pk_fma_f32 v[2:3], v[2:3], v[6:7], v[10:11]
	v_cvt_pk_bf16_f32 v226, v0, v1
	v_cvt_pk_bf16_f32 v227, v2, v3
	global_load_dwordx4 v[0:3], v[18:19], off
	s_nop 0
	global_load_dwordx4 v[4:7], v[50:51], off
	global_load_dwordx4 v[8:11], v[72:73], off
	global_store_dwordx2 v[46:47], v[226:227], off offset:1536
	v_pk_mul_f32 v[50:51], v[48:49], v[100:101] op_sel_hi:[0,1]
	v_pk_mul_f32 v[52:53], v[48:49], v[98:99] op_sel_hi:[0,1]
	s_waitcnt vmcnt(3)
	v_pk_mul_f32 v[0:1], v[50:51], v[0:1]
	s_waitcnt vmcnt(2)
	v_pk_add_f32 v[4:5], v[4:5], 1.0 op_sel_hi:[1,0]
	v_pk_mul_f32 v[2:3], v[52:53], v[2:3]
	v_pk_add_f32 v[6:7], v[6:7], 1.0 op_sel_hi:[1,0]
	s_waitcnt vmcnt(1)
	v_pk_fma_f32 v[0:1], v[0:1], v[4:5], v[8:9]
	v_pk_fma_f32 v[2:3], v[2:3], v[6:7], v[10:11]
	v_cvt_pk_bf16_f32 v226, v0, v1
	v_cvt_pk_bf16_f32 v227, v2, v3
	global_load_dwordx4 v[0:3], v[20:21], off
	s_nop 0
	global_load_dwordx4 v[4:7], v[56:57], off
	global_load_dwordx4 v[8:11], v[78:79], off
	global_store_dwordx2 v[46:47], v[226:227], off offset:2048
	v_pk_mul_f32 v[50:51], v[48:49], v[92:93] op_sel_hi:[0,1]
	v_pk_mul_f32 v[52:53], v[48:49], v[90:91] op_sel_hi:[0,1]
	s_waitcnt vmcnt(3)
	v_pk_mul_f32 v[0:1], v[50:51], v[0:1]
	s_waitcnt vmcnt(2)
	v_pk_add_f32 v[4:5], v[4:5], 1.0 op_sel_hi:[1,0]
	v_pk_mul_f32 v[2:3], v[52:53], v[2:3]
	v_pk_add_f32 v[6:7], v[6:7], 1.0 op_sel_hi:[1,0]
	s_waitcnt vmcnt(1)
	v_pk_fma_f32 v[0:1], v[0:1], v[4:5], v[8:9]
	v_pk_fma_f32 v[2:3], v[2:3], v[6:7], v[10:11]
	v_cvt_pk_bf16_f32 v226, v0, v1
	v_cvt_pk_bf16_f32 v227, v2, v3
	global_load_dwordx4 v[0:3], v[22:23], off
	s_nop 0
	global_load_dwordx4 v[4:7], v[58:59], off
	global_load_dwordx4 v[8:11], v[74:75], off
	global_store_dwordx2 v[46:47], v[226:227], off offset:2560
	v_pk_mul_f32 v[50:51], v[48:49], v[108:109] op_sel_hi:[0,1]
	v_pk_mul_f32 v[52:53], v[48:49], v[104:105] op_sel_hi:[0,1]
	s_waitcnt vmcnt(3)
	v_pk_mul_f32 v[0:1], v[50:51], v[0:1]
	s_waitcnt vmcnt(2)
	v_pk_add_f32 v[4:5], v[4:5], 1.0 op_sel_hi:[1,0]
	v_pk_mul_f32 v[2:3], v[52:53], v[2:3]
	v_pk_add_f32 v[6:7], v[6:7], 1.0 op_sel_hi:[1,0]
	s_waitcnt vmcnt(1)
	v_pk_fma_f32 v[0:1], v[0:1], v[4:5], v[8:9]
	v_pk_fma_f32 v[2:3], v[2:3], v[6:7], v[10:11]
	v_cvt_pk_bf16_f32 v226, v0, v1
	v_cvt_pk_bf16_f32 v227, v2, v3
	global_load_dwordx4 v[0:3], v[24:25], off
	s_nop 0
	global_load_dwordx4 v[4:7], v[60:61], off
	global_load_dwordx4 v[8:11], v[76:77], off
	global_store_dwordx2 v[46:47], v[226:227], off offset:3072
	v_pk_mul_f32 v[50:51], v[48:49], v[96:97] op_sel_hi:[0,1]
	v_pk_mul_f32 v[48:49], v[48:49], v[94:95] op_sel_hi:[0,1]
	s_waitcnt vmcnt(3)
	v_pk_mul_f32 v[0:1], v[50:51], v[0:1]
	s_waitcnt vmcnt(2)
	v_pk_add_f32 v[4:5], v[4:5], 1.0 op_sel_hi:[1,0]
	v_pk_mul_f32 v[2:3], v[48:49], v[2:3]
	v_pk_add_f32 v[6:7], v[6:7], 1.0 op_sel_hi:[1,0]
	s_waitcnt vmcnt(1)
	v_pk_fma_f32 v[0:1], v[0:1], v[4:5], v[8:9]
	v_pk_fma_f32 v[2:3], v[2:3], v[6:7], v[10:11]
	v_cvt_pk_bf16_f32 v226, v0, v1
	v_cvt_pk_bf16_f32 v227, v2, v3
	global_store_dwordx2 v[46:47], v[226:227], off offset:3584
	s_andn2_b64 exec, exec, s[10:11]
	s_cbranch_execnz .LBB0_1137

.LBB0_1139:
	s_cmp_gt_i32 s25, 8
	s_cselect_b64 s[6:7], -1, 0
	s_and_b64 s[0:1], s[0:1], s[6:7]
	s_andn2_b64 vcc, exec, s[0:1]
	s_cbranch_vccnz .LBB0_1193
	s_cmp_lg_u32 s32, 0
	s_addc_u32 s32, s32, 0
	s_waitcnt vmcnt(0)
	s_waitcnt vmcnt(0) lgkmcnt(0)
	s_barrier
	s_and_saveexec_b64 s[0:1], s[4:5]
	s_cbranch_execz .LBB0_1192
	s_cmp_lg_u32 s32, 0
	s_cbranch_scc1 .Lgb7
	s_add_i32 s2, 0, 0x23fe0
	v_mov_b32_e32 v0, s2
	s_waitcnt vmcnt(0) expcnt(0) lgkmcnt(0)
	ds_read_b32 v2, v0
	s_add_i32 s2, 0, 0x23fe4
	v_mov_b32_e32 v0, s2
	ds_read_b32 v0, v0
	s_waitcnt lgkmcnt(1)
	v_cmp_ne_u32_e32 vcc, 0, v2
	s_cbranch_vccnz .LBB0_1156
	s_add_u32 s8, s22, 0x1be4c300
	s_addc_u32 s9, s23, 0
	s_add_u32 s10, s22, 0x1be4c500
	s_addc_u32 s11, s23, 0
	s_add_u32 s12, s22, 0x1be4c600
	s_addc_u32 s13, s23, 0
	s_add_u32 s14, s22, 0x1be4c700
	s_addc_u32 s15, s23, 0
	s_add_u32 s16, s22, 0x1be4c800
	s_addc_u32 s17, s23, 0
	s_add_u32 s18, s22, 0x1be4c900
	s_addc_u32 s19, s23, 0
	s_add_u32 s30, s22, 0x1be4ca00
	s_addc_u32 s31, s23, 0
	s_add_u32 s34, s22, 0x1be4cb00
	s_addc_u32 s35, s23, 0
	s_add_u32 s36, s22, 0x1be4cc00
	s_addc_u32 s37, s23, 0
	s_add_u32 s38, s22, 0x1be4cd00
	s_addc_u32 s39, s23, 0
	s_add_u32 s40, s22, 0x1be4ce00
	s_addc_u32 s41, s23, 0
	s_add_u32 s42, s22, 0x1be4cf00
	s_addc_u32 s43, s23, 0
	s_add_u32 s44, s22, 0x1be4d000
	s_addc_u32 s45, s23, 0
	s_add_u32 s46, s22, 0x1be4d100
	s_addc_u32 s47, s23, 0
	s_add_u32 s48, s22, 0x1be4d200
	s_addc_u32 s49, s23, 0
	s_add_u32 s50, s22, 0x1be4d300
	s_addc_u32 s51, s23, 0
	s_mul_i32 s2, s27, s97
	s_add_u32 s52, s22, 0x1be4d400
	s_mul_i32 s2, s2, s26
	s_addc_u32 s53, s23, 0
	s_mov_b32 s33, 1
	v_mov_b32_e32 v16, 0
	s_branch .LBB0_1144

.LBB0_1209:
	s_cmp_gt_i32 s25, 9
	s_cselect_b64 s[6:7], -1, 0
	s_and_b64 s[0:1], s[0:1], s[6:7]
	s_andn2_b64 vcc, exec, s[0:1]
	s_cbranch_vccnz .LBB0_1263
	s_cmp_lg_u32 s32, 0
	s_addc_u32 s32, s32, 0
	s_waitcnt vmcnt(0)
	s_waitcnt vmcnt(0) lgkmcnt(0)
	s_barrier
	s_and_saveexec_b64 s[0:1], s[4:5]
	s_cbranch_execz .LBB0_1262
	s_cmp_lg_u32 s32, 0
	s_cbranch_scc1 .Lgb8
	s_add_i32 s2, 0, 0x23fe0
	v_mov_b32_e32 v0, s2
	s_waitcnt vmcnt(0) expcnt(0) lgkmcnt(0)
	ds_read_b32 v2, v0
	s_add_i32 s2, 0, 0x23fe4
	v_mov_b32_e32 v0, s2
	ds_read_b32 v0, v0
	s_waitcnt lgkmcnt(1)
	v_cmp_ne_u32_e32 vcc, 0, v2
	s_cbranch_vccnz .LBB0_1226
	s_add_u32 s8, s22, 0x1be4c300
	s_addc_u32 s9, s23, 0
	s_add_u32 s10, s22, 0x1be4c500
	s_addc_u32 s11, s23, 0
	s_add_u32 s12, s22, 0x1be4c600
	s_addc_u32 s13, s23, 0
	s_add_u32 s14, s22, 0x1be4c700
	s_addc_u32 s15, s23, 0
	s_add_u32 s16, s22, 0x1be4c800
	s_addc_u32 s17, s23, 0
	s_add_u32 s18, s22, 0x1be4c900
	s_addc_u32 s19, s23, 0
	s_add_u32 s30, s22, 0x1be4ca00
	s_addc_u32 s31, s23, 0
	s_add_u32 s34, s22, 0x1be4cb00
	s_addc_u32 s35, s23, 0
	s_add_u32 s36, s22, 0x1be4cc00
	s_addc_u32 s37, s23, 0
	s_add_u32 s38, s22, 0x1be4cd00
	s_addc_u32 s39, s23, 0
	s_add_u32 s40, s22, 0x1be4ce00
	s_addc_u32 s41, s23, 0
	s_add_u32 s42, s22, 0x1be4cf00
	s_addc_u32 s43, s23, 0
	s_add_u32 s44, s22, 0x1be4d000
	s_addc_u32 s45, s23, 0
	s_add_u32 s46, s22, 0x1be4d100
	s_addc_u32 s47, s23, 0
	s_add_u32 s48, s22, 0x1be4d200
	s_addc_u32 s49, s23, 0
	s_add_u32 s50, s22, 0x1be4d300
	s_addc_u32 s51, s23, 0
	s_mul_i32 s2, s27, s97
	s_add_u32 s52, s22, 0x1be4d400
	s_mul_i32 s2, s2, s26
	s_addc_u32 s53, s23, 0
	s_mov_b32 s33, 1
	v_mov_b32_e32 v16, 0
	s_branch .LBB0_1214

.LBB0_1291:
	s_cmp_gt_i32 s25, 10
	s_cselect_b64 s[0:1], -1, 0
	s_and_b64 s[6:7], s[6:7], s[0:1]
	s_andn2_b64 vcc, exec, s[6:7]
	s_cbranch_vccnz .LBB0_1345
	s_cmp_lg_u32 s32, 0
	s_addc_u32 s32, s32, 0
	s_waitcnt vmcnt(0)
	s_waitcnt vmcnt(0) lgkmcnt(0)
	s_barrier
	s_and_saveexec_b64 s[6:7], s[4:5]
	s_cbranch_execz .LBB0_1344
	s_cmp_lg_u32 s32, 0
	s_cbranch_scc1 .Lgb9
	s_add_i32 s2, 0, 0x23fe0
	v_mov_b32_e32 v0, s2
	s_waitcnt vmcnt(0) expcnt(0) lgkmcnt(0)
	ds_read_b32 v2, v0
	s_add_i32 s2, 0, 0x23fe4
	v_mov_b32_e32 v0, s2
	ds_read_b32 v0, v0
	s_waitcnt lgkmcnt(1)
	v_cmp_ne_u32_e32 vcc, 0, v2
	s_cbranch_vccnz .LBB0_1308
	s_add_u32 s4, s22, 0x1be4c300
	s_addc_u32 s5, s23, 0
	s_add_u32 s8, s22, 0x1be4c500
	s_addc_u32 s9, s23, 0
	s_add_u32 s10, s22, 0x1be4c600
	s_addc_u32 s11, s23, 0
	s_add_u32 s12, s22, 0x1be4c700
	s_addc_u32 s13, s23, 0
	s_add_u32 s14, s22, 0x1be4c800
	s_addc_u32 s15, s23, 0
	s_add_u32 s16, s22, 0x1be4c900
	s_addc_u32 s17, s23, 0
	s_add_u32 s18, s22, 0x1be4ca00
	s_addc_u32 s19, s23, 0
	s_add_u32 s30, s22, 0x1be4cb00
	s_addc_u32 s31, s23, 0
	s_add_u32 s34, s22, 0x1be4cc00
	s_addc_u32 s35, s23, 0
	s_add_u32 s36, s22, 0x1be4cd00
	s_addc_u32 s37, s23, 0
	s_add_u32 s38, s22, 0x1be4ce00
	s_addc_u32 s39, s23, 0
	s_add_u32 s40, s22, 0x1be4cf00
	s_addc_u32 s41, s23, 0
	s_add_u32 s42, s22, 0x1be4d000
	s_addc_u32 s43, s23, 0
	s_add_u32 s44, s22, 0x1be4d100
	s_addc_u32 s45, s23, 0
	s_add_u32 s46, s22, 0x1be4d200
	s_addc_u32 s47, s23, 0
	s_add_u32 s48, s22, 0x1be4d300
	s_addc_u32 s49, s23, 0
	s_mul_i32 s2, s27, s97
	s_add_u32 s50, s22, 0x1be4d400
	s_mul_i32 s2, s2, s26
	s_addc_u32 s51, s23, 0
	s_mov_b32 s25, 1
	v_mov_b32_e32 v16, 0
	s_branch .LBB0_1296

.LBB0_1343:
	s_or_b64 exec, exec, s[10:11]
	s_waitcnt vmcnt(0)
	s_branch .LBB0_1344

.LBB0_1345:
	s_cmp_lt_i32 s24, 11
	s_cselect_b64 s[4:5], -1, 0
	s_and_b64 s[0:1], s[4:5], s[0:1]
	s_andn2_b64 vcc, exec, s[0:1]
	s_cbranch_vccnz .LBB0_1349
	s_waitcnt vmcnt(0)
	v_and_b32_e32 v0, 60, v145
	s_and_b32 s98, s3, 7
	s_lshl_b32 s98, s98, 11
	s_bfe_u32 s99, s3, 0x30003
	s_lshl_b32 s99, s99, 8
	s_or_b32 s98, s98, s99
	s_lshr_b32 s99, s3, 6
	s_lshl_b32 s99, s99, 6
	s_or_b32 s98, s98, s99
	v_add_u32_e32 v4, s98, v0
	s_movk_i32 s0, 0x4000
	v_cmp_gt_i32_e32 vcc, s0, v4
	s_and_saveexec_b64 s[0:1], vcc
	s_cbranch_execz .LBB0_1349
	v_mbcnt_lo_u32_b32 v1, -1, 0
	v_mbcnt_hi_u32_b32 v1, -1, v1
	v_and_b32_e32 v2, 64, v1
	v_add_u32_e32 v2, 64, v2
	v_xor_b32_e32 v3, 32, v1
	v_cmp_lt_i32_e32 vcc, v3, v2
	v_lshlrev_b32_e32 v0, 2, v144
	v_readlane_b32 s4, v248, 0
	v_cndmask_b32_e32 v3, v1, v3, vcc
	v_lshlrev_b32_e32 v132, 2, v3
	v_xor_b32_e32 v3, 16, v1
	v_cmp_lt_i32_e32 vcc, v3, v2
	v_and_b32_e32 v0, 0xfc, v0
	v_readlane_b32 s6, v248, 2
	v_cndmask_b32_e32 v3, v1, v3, vcc
	v_lshlrev_b32_e32 v133, 2, v3
	v_xor_b32_e32 v3, 8, v1
	v_cmp_lt_i32_e32 vcc, v3, v2
	v_readlane_b32 s7, v248, 3
	v_readlane_b32 s10, v248, 6
	v_cndmask_b32_e32 v3, v1, v3, vcc
	v_lshlrev_b32_e32 v134, 2, v3
	v_xor_b32_e32 v3, 4, v1
	v_cmp_lt_i32_e32 vcc, v3, v2
	v_readlane_b32 s11, v248, 7
	v_mov_b32_e32 v7, 0
	v_cndmask_b32_e32 v3, v1, v3, vcc
	v_lshlrev_b32_e32 v135, 2, v3
	v_xor_b32_e32 v3, 2, v1
	v_cmp_lt_i32_e32 vcc, v3, v2
	v_lshlrev_b32_e32 v6, 2, v0
	s_mov_b64 s[6:7], s[10:11]
	v_cndmask_b32_e32 v3, v1, v3, vcc
	v_lshlrev_b32_e32 v136, 2, v3
	v_xor_b32_e32 v3, 1, v1
	v_cmp_lt_i32_e32 vcc, v3, v2
	v_or_b32_e32 v2, 0x400, v0
	v_or_b32_e32 v22, 0x500, v0
	v_lshl_add_u64 v[8:9], s[6:7], 0, v[6:7]
	v_lshlrev_b32_e32 v6, 2, v2
	v_or_b32_e32 v24, 0x600, v0
	v_lshl_add_u64 v[10:11], s[6:7], 0, v[6:7]
	v_lshlrev_b32_e32 v6, 2, v22
	v_or_b32_e32 v26, 0x700, v0
	v_lshl_add_u64 v[12:13], s[6:7], 0, v[6:7]
	v_lshlrev_b32_e32 v6, 2, v24
	v_lshl_add_u64 v[14:15], s[6:7], 0, v[6:7]
	v_lshlrev_b32_e32 v6, 2, v26
	v_lshl_add_u64 v[16:17], s[6:7], 0, v[6:7]
	v_lshlrev_b32_e32 v6, 1, v0
	v_cndmask_b32_e32 v1, v1, v3, vcc
	v_readlane_b32 s5, v248, 1
	v_lshl_add_u64 v[18:19], s[22:23], 0, v[6:7]
	s_mov_b64 s[0:1], 0x16a00000
	s_mov_b32 s4, 0x358637bd
	v_lshlrev_b32_e32 v137, 2, v1
	s_lshl_b32 s3, s26, 5
	v_lshl_add_u64 v[18:19], v[18:19], 0, s[0:1]
	s_mov_b64 s[0:1], 0
	v_lshlrev_b32_e32 v6, 2, v0
	v_lshlrev_b32_e32 v20, 2, v2
	v_mov_b32_e32 v21, v7
	v_lshlrev_b32_e32 v22, 2, v22
	v_mov_b32_e32 v23, v7
	v_lshlrev_b32_e32 v24, 2, v24
	v_mov_b32_e32 v25, v7
	v_lshlrev_b32_e32 v26, 2, v26
	v_mov_b32_e32 v27, v7
	s_mov_b32 s2, 0x3a000000
	v_mov_b64_e32 v[28:29], s[4:5]
	s_mov_b32 s4, 0x800000
	s_movk_i32 s5, 0x3fff
	v_readlane_b32 s8, v248, 4
	v_readlane_b32 s9, v248, 5
	global_load_dwordx4 v[180:183], v[8:9], off
	global_load_dwordx4 v[184:187], v[8:9], off offset:1024
	global_load_dwordx4 v[188:191], v[8:9], off offset:2048
	global_load_dwordx4 v[192:195], v[8:9], off offset:3072
	global_load_dwordx4 v[196:199], v[10:11], off
	global_load_dwordx4 v[200:203], v[12:13], off
	global_load_dwordx4 v[204:207], v[14:15], off
	global_load_dwordx4 v[208:211], v[16:17], off
.LBB0_1348:
	v_ashrrev_i32_e32 v5, 31, v4
	v_lshlrev_b64 v[0:1], 12, v[4:5]
	v_lshl_add_u64 v[0:1], v[18:19], 0, v[0:1]
	v_add_u32_e32 v48, 1, v4
	global_load_dwordx2 v[30:31], v[0:1], off offset:2560
	global_load_dwordx2 v[32:33], v[0:1], off offset:2048
	global_load_dwordx2 v[34:35], v[0:1], off offset:3584
	global_load_dwordx2 v[36:37], v[0:1], off offset:3072
	global_load_dwordx2 v[38:39], v[0:1], off
	global_load_dwordx2 v[40:41], v[0:1], off offset:512
	global_load_dwordx2 v[42:43], v[0:1], off offset:1024
	v_ashrrev_i32_e32 v49, 31, v48
	global_load_dwordx2 v[44:45], v[0:1], off offset:1536
	v_lshlrev_b64 v[0:1], 12, v[48:49]
	v_lshl_add_u64 v[46:47], v[18:19], 0, v[0:1]
	global_load_dwordx2 v[52:53], v[46:47], off offset:2560
	global_load_dwordx2 v[54:55], v[46:47], off offset:2048
	global_load_dwordx2 v[56:57], v[46:47], off
	global_load_dwordx2 v[58:59], v[46:47], off offset:512
	global_load_dwordx2 v[60:61], v[46:47], off offset:1024
	global_load_dwordx2 v[62:63], v[46:47], off offset:1536
	global_load_dwordx4 v[0:3], v[8:9], off
	global_load_dwordx2 v[64:65], v[46:47], off offset:3072
	global_load_dwordx2 v[72:73], v[46:47], off offset:3584
	v_lshlrev_b64 v[48:49], 13, v[48:49]
	v_lshl_add_u64 v[48:49], s[20:21], 0, v[48:49]
	s_waitcnt vmcnt(0)
	v_and_b32_e32 v123, 0xffff0000, v30
	v_and_b32_e32 v122, 0xffff0000, v32
	v_lshlrev_b32_e32 v101, 16, v34
	v_and_b32_e32 v51, 0xffff0000, v52
	v_and_b32_e32 v50, 0xffff0000, v54
	v_and_b32_e32 v95, 0xffff0000, v34
	v_lshlrev_b32_e32 v109, 16, v35
	v_and_b32_e32 v111, 0xffff0000, v35
	v_lshlrev_b32_e32 v67, 16, v52
	v_lshlrev_b32_e32 v66, 16, v54
	v_pk_mul_f32 v[34:35], v[50:51], v[50:51]
	v_lshlrev_b32_e32 v69, 16, v53
	v_lshlrev_b32_e32 v68, 16, v55
	v_pk_fma_f32 v[34:35], v[66:67], v[66:67], v[34:35]
	v_and_b32_e32 v99, 0xffff0000, v38
	v_and_b32_e32 v93, 0xffff0000, v40
	v_and_b32_e32 v71, 0xffff0000, v53
	v_and_b32_e32 v70, 0xffff0000, v55
	v_and_b32_e32 v98, 0xffff0000, v56
	v_and_b32_e32 v92, 0xffff0000, v58
	v_pk_fma_f32 v[34:35], v[68:69], v[68:69], v[34:35]
	v_lshlrev_b32_e32 v100, 16, v36
	v_and_b32_e32 v94, 0xffff0000, v36
	v_lshlrev_b32_e32 v108, 16, v37
	v_and_b32_e32 v110, 0xffff0000, v37
	v_lshlrev_b32_e32 v87, 16, v38
	v_lshlrev_b32_e32 v85, 16, v40
	v_lshlrev_b32_e32 v83, 16, v42
	v_and_b32_e32 v91, 0xffff0000, v42
	v_lshlrev_b32_e32 v97, 16, v43
	v_and_b32_e32 v107, 0xffff0000, v43
	v_lshlrev_b32_e32 v86, 16, v56
	v_lshlrev_b32_e32 v84, 16, v58
	v_pk_fma_f32 v[42:43], v[70:71], v[70:71], v[34:35]
	v_pk_mul_f32 v[34:35], v[98:99], v[98:99]
	v_pk_mul_f32 v[36:37], v[92:93], v[92:93]
	v_lshlrev_b32_e32 v105, 16, v39
	v_lshlrev_b32_e32 v103, 16, v41
	v_lshlrev_b32_e32 v104, 16, v57
	v_lshlrev_b32_e32 v102, 16, v59
	v_pk_fma_f32 v[34:35], v[86:87], v[86:87], v[34:35]
	v_pk_fma_f32 v[36:37], v[84:85], v[84:85], v[36:37]
	v_and_b32_e32 v117, 0xffff0000, v39
	v_and_b32_e32 v113, 0xffff0000, v41
	v_and_b32_e32 v116, 0xffff0000, v57
	v_and_b32_e32 v112, 0xffff0000, v59
	v_pk_fma_f32 v[34:35], v[104:105], v[104:105], v[34:35]
	v_pk_fma_f32 v[36:37], v[102:103], v[102:103], v[36:37]
	v_and_b32_e32 v90, 0xffff0000, v60
	v_pk_fma_f32 v[34:35], v[116:117], v[116:117], v[34:35]
	v_pk_fma_f32 v[36:37], v[112:113], v[112:113], v[36:37]
	v_lshlrev_b32_e32 v82, 16, v60
	v_pk_add_f32 v[34:35], v[34:35], v[36:37]
	v_pk_mul_f32 v[36:37], v[90:91], v[90:91]
	v_lshlrev_b32_e32 v96, 16, v61
	v_pk_fma_f32 v[36:37], v[82:83], v[82:83], v[36:37]
	v_and_b32_e32 v106, 0xffff0000, v61
	v_pk_fma_f32 v[36:37], v[96:97], v[96:97], v[36:37]
	v_and_b32_e32 v89, 0xffff0000, v44
	v_and_b32_e32 v88, 0xffff0000, v62
	v_pk_fma_f32 v[36:37], v[106:107], v[106:107], v[36:37]
	v_lshlrev_b32_e32 v125, 16, v30
	v_lshlrev_b32_e32 v124, 16, v32
	v_lshlrev_b32_e32 v127, 16, v31
	v_and_b32_e32 v129, 0xffff0000, v31
	v_lshlrev_b32_e32 v81, 16, v44
	v_pk_mul_f32 v[30:31], v[122:123], v[122:123]
	v_lshlrev_b32_e32 v80, 16, v62
	v_pk_add_f32 v[34:35], v[34:35], v[36:37]
	v_pk_mul_f32 v[36:37], v[88:89], v[88:89]
	v_lshlrev_b32_e32 v126, 16, v33
	v_lshlrev_b32_e32 v120, 16, v63
	v_pk_fma_f32 v[30:31], v[124:125], v[124:125], v[30:31]
	v_lshlrev_b32_e32 v121, 16, v45
	v_pk_fma_f32 v[36:37], v[80:81], v[80:81], v[36:37]
	v_and_b32_e32 v128, 0xffff0000, v33
	v_pk_fma_f32 v[30:31], v[126:127], v[126:127], v[30:31]
	v_and_b32_e32 v131, 0xffff0000, v45
	v_and_b32_e32 v130, 0xffff0000, v63
	v_pk_fma_f32 v[36:37], v[120:121], v[120:121], v[36:37]
	v_pk_fma_f32 v[30:31], v[128:129], v[128:129], v[30:31]
	v_pk_fma_f32 v[36:37], v[130:131], v[130:131], v[36:37]
	v_pk_mul_f32 v[32:33], v[94:95], v[94:95]
	v_pk_add_f32 v[34:35], v[34:35], v[36:37]
	v_mov_b32_e32 v36, v42
	v_mov_b32_e32 v37, v30
	v_pk_add_f32 v[44:45], v[34:35], v[36:37]
	v_and_b32_e32 v35, 0xffff0000, v72
	v_and_b32_e32 v34, 0xffff0000, v64
	v_lshlrev_b32_e32 v41, 16, v72
	v_lshlrev_b32_e32 v40, 16, v64
	v_pk_mul_f32 v[46:47], v[34:35], v[34:35]
	v_pk_fma_f32 v[32:33], v[100:101], v[100:101], v[32:33]
	v_lshlrev_b32_e32 v37, 16, v73
	v_lshlrev_b32_e32 v36, 16, v65
	v_pk_fma_f32 v[46:47], v[40:41], v[40:41], v[46:47]
	v_pk_fma_f32 v[32:33], v[108:109], v[108:109], v[32:33]
	v_and_b32_e32 v39, 0xffff0000, v73
	v_and_b32_e32 v38, 0xffff0000, v65
	v_pk_fma_f32 v[46:47], v[36:37], v[36:37], v[46:47]
	v_pk_fma_f32 v[32:33], v[110:111], v[110:111], v[32:33]
	v_pk_fma_f32 v[46:47], v[38:39], v[38:39], v[46:47]
	v_mov_b32_e32 v30, v43
	v_pk_add_f32 v[30:31], v[44:45], v[30:31]
	v_mov_b32_e32 v42, v46
	v_mov_b32_e32 v43, v32
	v_pk_add_f32 v[30:31], v[30:31], v[42:43]
	v_mov_b32_e32 v32, v47
	v_pk_add_f32 v[30:31], v[30:31], v[32:33]
	ds_bpermute_b32 v43, v132, v31
	ds_bpermute_b32 v42, v132, v30
	v_add_u32_e32 v32, 2, v4
	v_ashrrev_i32_e32 v33, 31, v32
	v_lshlrev_b64 v[44:45], 12, v[32:33]
	v_lshl_add_u64 v[44:45], v[18:19], 0, v[44:45]
	s_waitcnt lgkmcnt(0)
	v_pk_add_f32 v[30:31], v[30:31], v[42:43]
	ds_bpermute_b32 v43, v133, v31
	ds_bpermute_b32 v42, v133, v30
	global_load_dwordx2 v[60:61], v[44:45], off
	global_load_dwordx2 v[56:57], v[44:45], off offset:512
	global_load_dwordx2 v[52:53], v[44:45], off offset:1024
	global_load_dwordx2 v[46:47], v[44:45], off offset:1536
	global_load_dwordx2 v[114:115], v[44:45], off offset:2048
	global_load_dwordx2 v[118:119], v[44:45], off offset:2560
	global_load_dwordx2 v[74:75], v[44:45], off offset:3072
	global_load_dwordx2 v[78:79], v[44:45], off offset:3584
	v_mov_b32_e32 v146, v87
	v_mov_b32_e32 v147, v99
	s_waitcnt lgkmcnt(0)
	v_pk_add_f32 v[30:31], v[30:31], v[42:43]
	ds_bpermute_b32 v43, v134, v31
	ds_bpermute_b32 v42, v134, v30
	v_mov_b32_e32 v148, v105
	v_mov_b32_e32 v149, v117
	v_mov_b32_e32 v87, v98
	v_mov_b32_e32 v105, v116
	s_waitcnt lgkmcnt(0)
	v_pk_add_f32 v[42:43], v[30:31], v[42:43]
	ds_bpermute_b32 v45, v135, v43
	ds_bpermute_b32 v44, v135, v42
	v_add_u32_e32 v30, 3, v4
	v_ashrrev_i32_e32 v31, 31, v30
	v_lshlrev_b64 v[54:55], 12, v[30:31]
	v_lshl_add_u64 v[138:139], v[18:19], 0, v[54:55]
	s_waitcnt lgkmcnt(0)
	v_pk_add_f32 v[42:43], v[42:43], v[44:45]
	ds_bpermute_b32 v45, v136, v43
	ds_bpermute_b32 v44, v136, v42
	global_load_dwordx2 v[64:65], v[138:139], off
	global_load_dwordx2 v[62:63], v[138:139], off offset:512
	global_load_dwordx2 v[58:59], v[138:139], off offset:1024
	global_load_dwordx2 v[54:55], v[138:139], off offset:1536
	v_lshlrev_b64 v[32:33], 13, v[32:33]
	v_lshlrev_b64 v[30:31], 13, v[30:31]
	s_waitcnt lgkmcnt(0)
	v_pk_add_f32 v[140:141], v[42:43], v[44:45]
	ds_bpermute_b32 v143, v137, v141
	ds_bpermute_b32 v142, v137, v140
	global_load_dwordx2 v[72:73], v[138:139], off offset:2048
	global_load_dwordx2 v[76:77], v[138:139], off offset:2560
	global_load_dwordx2 v[42:43], v[138:139], off offset:3072
	global_load_dwordx2 v[44:45], v[138:139], off offset:3584
	s_waitcnt lgkmcnt(0)
	v_pk_add_f32 v[138:139], v[140:141], v[142:143]
	s_nop 0
	v_pk_fma_f32 v[138:139], v[138:139], s[2:3], v[28:29] op_sel_hi:[1,0,0]
	s_nop 0
	v_mul_f32_e32 v140, 0x4b800000, v139
	v_cmp_gt_f32_e32 vcc, s4, v139
	s_nop 1
	v_cndmask_b32_e32 v139, v139, v140, vcc
	v_rsq_f32_e32 v139, v139
	v_lshlrev_b64 v[140:141], 13, v[4:5]
	v_lshl_add_u64 v[140:141], s[20:21], 0, v[140:141]
	v_lshl_add_u64 v[142:143], v[140:141], 0, v[6:7]
	v_mul_f32_e32 v5, 0x45800000, v139
	v_cndmask_b32_e32 v144, v139, v5, vcc
	v_pk_mul_f32 v[146:147], v[146:147], v[144:145] op_sel_hi:[1,0]
	v_pk_mul_f32 v[148:149], v[148:149], v[144:145] op_sel_hi:[1,0]
	v_pk_mul_f32 v[0:1], v[0:1], v[146:147]
	v_pk_mul_f32 v[2:3], v[2:3], v[148:149]
	global_store_dwordx4 v[142:143], v[0:3], off nt
	v_mov_b32_e32 v146, v103
	v_mov_b32_e32 v147, v113
	v_mov_b32_e32 v148, v85
	v_mov_b32_e32 v149, v93
	v_pk_mul_f32 v[146:147], v[146:147], v[144:145] op_sel_hi:[1,0]
	v_pk_mul_f32 v[148:149], v[148:149], v[144:145] op_sel_hi:[1,0]
	v_mul_f32_e32 v5, 0x4b800000, v138
	v_cmp_gt_f32_e32 vcc, s4, v138
	v_mov_b32_e32 v85, v92
	v_mov_b32_e32 v103, v112
	v_cndmask_b32_e32 v5, v138, v5, vcc
	v_rsq_f32_e32 v5, v5
	v_add_u32_e32 v4, 32, v4
	s_waitcnt vmcnt(12)
	v_lshlrev_b32_e32 v92, 16, v115
	s_waitcnt vmcnt(11)
	v_lshlrev_b32_e32 v93, 16, v119
	s_waitcnt vmcnt(1)
	v_pk_mul_f32 v[0:1], v[184:185], v[148:149]
	v_pk_mul_f32 v[2:3], v[186:187], v[146:147]
	global_store_dwordx4 v[142:143], v[0:3], off offset:1024 nt
	v_mov_b32_e32 v146, v97
	v_mov_b32_e32 v147, v107
	v_mov_b32_e32 v148, v83
	v_mov_b32_e32 v149, v91
	v_pk_mul_f32 v[146:147], v[146:147], v[144:145] op_sel_hi:[1,0]
	v_pk_mul_f32 v[148:149], v[148:149], v[144:145] op_sel_hi:[1,0]
	v_mov_b32_e32 v83, v90
	v_mov_b32_e32 v97, v106
	v_lshlrev_b32_e32 v90, 16, v65
	v_lshlrev_b32_e32 v91, 16, v61
	s_waitcnt vmcnt(2)
	v_pk_mul_f32 v[0:1], v[188:189], v[148:149]
	v_pk_mul_f32 v[2:3], v[190:191], v[146:147]
	global_store_dwordx4 v[142:143], v[0:3], off offset:2048 nt
	v_mov_b32_e32 v146, v121
	v_mov_b32_e32 v147, v131
	v_mov_b32_e32 v148, v81
	v_mov_b32_e32 v149, v89
	v_pk_mul_f32 v[146:147], v[146:147], v[144:145] op_sel_hi:[1,0]
	v_pk_mul_f32 v[148:149], v[148:149], v[144:145] op_sel_hi:[1,0]
	v_mul_f32_e32 v81, 0x45800000, v5
	v_mov_b32_e32 v121, v130
	v_lshlrev_b32_e32 v89, 16, v57
	s_waitcnt vmcnt(3)
	v_pk_mul_f32 v[0:1], v[192:193], v[148:149]
	v_pk_mul_f32 v[2:3], v[194:195], v[146:147]
	global_store_dwordx4 v[142:143], v[0:3], off offset:3072 nt
	v_mov_b32_e32 v146, v126
	v_mov_b32_e32 v147, v128
	v_mov_b32_e32 v148, v124
	v_mov_b32_e32 v149, v122
	v_pk_mul_f32 v[146:147], v[146:147], v[144:145] op_sel_hi:[1,0]
	v_pk_mul_f32 v[148:149], v[148:149], v[144:145] op_sel_hi:[1,0]
	v_lshl_add_u64 v[142:143], v[140:141], 0, v[20:21]
	v_mov_b32_e32 v122, v125
	v_mov_b32_e32 v128, v127
	v_pk_mul_f32 v[124:125], v[128:129], v[144:145] op_sel_hi:[1,0]
	v_pk_mul_f32 v[122:123], v[122:123], v[144:145] op_sel_hi:[1,0]
	v_mov_b32_e32 v126, v100
	v_mov_b32_e32 v127, v94
	v_pk_mul_f32 v[126:127], v[126:127], v[144:145] op_sel_hi:[1,0]
	v_mov_b32_e32 v94, v101
	v_pk_mul_f32 v[94:95], v[94:95], v[144:145] op_sel_hi:[1,0]
	s_waitcnt vmcnt(4)
	v_pk_mul_f32 v[0:1], v[196:197], v[148:149]
	v_pk_mul_f32 v[2:3], v[198:199], v[146:147]
	global_store_dwordx4 v[142:143], v[0:3], off nt
	v_lshl_add_u64 v[142:143], v[140:141], 0, v[22:23]
	s_waitcnt vmcnt(5)
	v_pk_mul_f32 v[0:1], v[200:201], v[122:123]
	v_pk_mul_f32 v[2:3], v[202:203], v[124:125]
	global_store_dwordx4 v[142:143], v[0:3], off nt
	v_mov_b32_e32 v124, v108
	v_mov_b32_e32 v125, v110
	v_pk_mul_f32 v[124:125], v[124:125], v[144:145] op_sel_hi:[1,0]
	v_lshl_add_u64 v[122:123], v[140:141], 0, v[24:25]
	v_mov_b32_e32 v110, v109
	v_pk_mul_f32 v[100:101], v[110:111], v[144:145] op_sel_hi:[1,0]
	v_cndmask_b32_e32 v108, v5, v81, vcc
	v_pk_mul_f32 v[98:99], v[104:105], v[108:109] op_sel_hi:[1,0]
	v_pk_mul_f32 v[86:87], v[86:87], v[108:109] op_sel_hi:[1,0]
	v_pk_mul_f32 v[84:85], v[84:85], v[108:109] op_sel_hi:[1,0]
	v_pk_mul_f32 v[82:83], v[82:83], v[108:109] op_sel_hi:[1,0]
	v_mov_b32_e32 v81, v88
	v_pk_mul_f32 v[80:81], v[80:81], v[108:109] op_sel_hi:[1,0]
	v_lshl_add_u64 v[110:111], v[48:49], 0, v[26:27]
	v_lshlrev_b32_e32 v88, 16, v63
	s_waitcnt vmcnt(6)
	v_pk_mul_f32 v[0:1], v[126:127], v[204:205]
	v_pk_mul_f32 v[2:3], v[124:125], v[206:207]
	global_store_dwordx4 v[122:123], v[0:3], off nt
	v_lshl_add_u64 v[122:123], v[140:141], 0, v[26:27]
	s_waitcnt vmcnt(7)
	v_pk_mul_f32 v[0:1], v[94:95], v[208:209]
	v_pk_mul_f32 v[2:3], v[100:101], v[210:211]
	global_store_dwordx4 v[122:123], v[0:3], off nt
	v_lshl_add_u64 v[94:95], v[48:49], 0, v[6:7]
	v_and_b32_e32 v100, 0xffff0000, v63
	v_and_b32_e32 v63, 0xffff0000, v52
	v_and_b32_e32 v101, 0xffff0000, v57
	v_lshlrev_b32_e32 v57, 16, v46
	s_waitcnt vmcnt(8)
	v_pk_mul_f32 v[0:1], v[180:181], v[86:87]
	v_pk_mul_f32 v[2:3], v[182:183], v[98:99]
	global_store_dwordx4 v[94:95], v[0:3], off nt
	v_pk_mul_f32 v[86:87], v[102:103], v[108:109] op_sel_hi:[1,0]
	v_and_b32_e32 v98, 0xffff0000, v115
	v_and_b32_e32 v102, 0xffff0000, v65
	v_lshlrev_b32_e32 v65, 16, v56
	v_and_b32_e32 v99, 0xffff0000, v119
	v_and_b32_e32 v103, 0xffff0000, v61
	v_lshlrev_b32_e32 v61, 16, v52
	v_and_b32_e32 v52, 0xffff0000, v42
	s_waitcnt vmcnt(9)
	v_pk_mul_f32 v[0:1], v[184:185], v[84:85]
	v_pk_mul_f32 v[2:3], v[186:187], v[86:87]
	global_store_dwordx4 v[94:95], v[0:3], off offset:1024 nt
	v_pk_mul_f32 v[84:85], v[96:97], v[108:109] op_sel_hi:[1,0]
	v_and_b32_e32 v87, 0xffff0000, v60
	v_and_b32_e32 v86, 0xffff0000, v64
	v_and_b32_e32 v96, 0xffff0000, v59
	v_and_b32_e32 v97, 0xffff0000, v53
	s_waitcnt vmcnt(10)
	v_pk_mul_f32 v[0:1], v[188:189], v[82:83]
	v_pk_mul_f32 v[2:3], v[190:191], v[84:85]
	global_store_dwordx4 v[94:95], v[0:3], off offset:2048 nt
	v_pk_mul_f32 v[82:83], v[120:121], v[108:109] op_sel_hi:[1,0]
	v_mov_b32_e32 v84, v66
	v_mov_b32_e32 v85, v50
	v_pk_mul_f32 v[84:85], v[84:85], v[108:109] op_sel_hi:[1,0]
	v_mov_b32_e32 v50, v67
	v_pk_mul_f32 v[50:51], v[50:51], v[108:109] op_sel_hi:[1,0]
	s_waitcnt vmcnt(11)
	v_pk_mul_f32 v[0:1], v[192:193], v[80:81]
	v_pk_mul_f32 v[2:3], v[194:195], v[82:83]
	global_store_dwordx4 v[94:95], v[0:3], off offset:3072 nt
	v_mov_b32_e32 v82, v68
	v_mov_b32_e32 v83, v70
	v_pk_mul_f32 v[82:83], v[82:83], v[108:109] op_sel_hi:[1,0]
	v_lshl_add_u64 v[80:81], v[48:49], 0, v[20:21]
	v_mov_b32_e32 v70, v69
	v_pk_mul_f32 v[66:67], v[70:71], v[108:109] op_sel_hi:[1,0]
	v_mov_b32_e32 v68, v40
	v_mov_b32_e32 v69, v34
	v_pk_mul_f32 v[68:69], v[68:69], v[108:109] op_sel_hi:[1,0]
	v_mov_b32_e32 v34, v41
	v_pk_mul_f32 v[34:35], v[34:35], v[108:109] op_sel_hi:[1,0]
	v_lshlrev_b32_e32 v71, 16, v60
	v_lshlrev_b32_e32 v70, 16, v64
	v_lshlrev_b32_e32 v64, 16, v62
	v_lshlrev_b32_e32 v60, 16, v58
	v_and_b32_e32 v95, 0xffff0000, v47
	v_and_b32_e32 v94, 0xffff0000, v55
	s_waitcnt vmcnt(12)
	v_pk_mul_f32 v[0:1], v[196:197], v[84:85]
	v_pk_mul_f32 v[2:3], v[198:199], v[82:83]
	global_store_dwordx4 v[80:81], v[0:3], off nt
	v_lshl_add_u64 v[80:81], v[48:49], 0, v[22:23]
	v_lshlrev_b32_e32 v82, 16, v75
	v_lshlrev_b32_e32 v84, 16, v114
	v_lshlrev_b32_e32 v85, 16, v118
	v_lshlrev_b32_e32 v83, 16, v79
	v_and_b32_e32 v79, 0xffff0000, v79
	s_waitcnt vmcnt(13)
	v_pk_mul_f32 v[0:1], v[200:201], v[50:51]
	v_pk_mul_f32 v[2:3], v[202:203], v[66:67]
	global_store_dwordx4 v[80:81], v[0:3], off nt
	v_lshl_add_u64 v[50:51], v[48:49], 0, v[24:25]
	v_mov_b32_e32 v48, v36
	v_mov_b32_e32 v49, v38
	v_pk_mul_f32 v[48:49], v[48:49], v[108:109] op_sel_hi:[1,0]
	v_mov_b32_e32 v38, v37
	v_pk_mul_f32 v[36:37], v[38:39], v[108:109] op_sel_hi:[1,0]
	v_lshlrev_b32_e32 v67, 16, v78
	v_lshlrev_b32_e32 v66, 16, v74
	v_and_b32_e32 v80, 0xffff0000, v114
	v_pk_mul_f32 v[114:115], v[86:87], v[86:87]
	v_and_b32_e32 v81, 0xffff0000, v118
	v_pk_fma_f32 v[114:115], v[70:71], v[70:71], v[114:115]
	v_pk_mul_f32 v[40:41], v[80:81], v[80:81]
	v_pk_fma_f32 v[114:115], v[90:91], v[90:91], v[114:115]
	v_pk_fma_f32 v[40:41], v[84:85], v[84:85], v[40:41]
	s_waitcnt vmcnt(14)
	v_pk_mul_f32 v[0:1], v[68:69], v[204:205]
	v_pk_mul_f32 v[2:3], v[48:49], v[206:207]
	global_store_dwordx4 v[50:51], v[0:3], off nt
	v_and_b32_e32 v69, 0xffff0000, v78
	v_and_b32_e32 v68, 0xffff0000, v74
	v_and_b32_e32 v78, 0xffff0000, v75
	v_and_b32_e32 v3, 0xffff0000, v76
	v_and_b32_e32 v2, 0xffff0000, v72
	v_and_b32_e32 v75, 0xffff0000, v56
	v_and_b32_e32 v74, 0xffff0000, v62
	v_lshlrev_b32_e32 v1, 16, v76
	v_lshlrev_b32_e32 v0, 16, v72
	v_and_b32_e32 v62, 0xffff0000, v58
	v_pk_mul_f32 v[112:113], v[2:3], v[2:3]
	v_pk_mul_f32 v[116:117], v[74:75], v[74:75]
	v_lshlrev_b32_e32 v49, 16, v77
	v_lshlrev_b32_e32 v48, 16, v73
	v_lshlrev_b32_e32 v76, 16, v59
	v_and_b32_e32 v59, 0xffff0000, v46
	v_and_b32_e32 v58, 0xffff0000, v54
	v_pk_mul_f32 v[118:119], v[62:63], v[62:63]
	v_pk_fma_f32 v[112:113], v[0:1], v[0:1], v[112:113]
	v_pk_fma_f32 v[116:117], v[64:65], v[64:65], v[116:117]
	v_and_b32_e32 v51, 0xffff0000, v77
	v_and_b32_e32 v50, 0xffff0000, v73
	v_lshlrev_b32_e32 v77, 16, v53
	v_lshlrev_b32_e32 v56, 16, v54
	v_pk_mul_f32 v[120:121], v[58:59], v[58:59]
	v_pk_fma_f32 v[118:119], v[60:61], v[60:61], v[118:119]
	v_pk_fma_f32 v[112:113], v[48:49], v[48:49], v[112:113]
	v_pk_fma_f32 v[38:39], v[88:89], v[88:89], v[116:117]
	v_lshlrev_b32_e32 v73, 16, v47
	v_lshlrev_b32_e32 v72, 16, v55
	v_and_b32_e32 v53, 0xffff0000, v44
	v_pk_fma_f32 v[120:121], v[56:57], v[56:57], v[120:121]
	v_pk_fma_f32 v[38:39], v[100:101], v[100:101], v[38:39]
	v_lshlrev_b32_e32 v47, 16, v44
	v_lshlrev_b32_e32 v46, 16, v42
	v_lshlrev_b32_e32 v54, 16, v43
	v_and_b32_e32 v44, 0xffff0000, v43
	v_pk_mul_f32 v[42:43], v[68:69], v[68:69]
	v_pk_mul_f32 v[122:123], v[52:53], v[52:53]
	v_pk_fma_f32 v[40:41], v[92:93], v[92:93], v[40:41]
	v_lshlrev_b32_e32 v55, 16, v45
	v_pk_fma_f32 v[42:43], v[66:67], v[66:67], v[42:43]
	v_pk_fma_f32 v[122:123], v[46:47], v[46:47], v[122:123]
	v_pk_fma_f32 v[40:41], v[98:99], v[98:99], v[40:41]
	v_and_b32_e32 v45, 0xffff0000, v45
	v_pk_fma_f32 v[42:43], v[82:83], v[82:83], v[42:43]
	v_pk_fma_f32 v[108:109], v[54:55], v[54:55], v[122:123]
	v_pk_fma_f32 v[42:43], v[78:79], v[78:79], v[42:43]
	v_pk_fma_f32 v[108:109], v[44:45], v[44:45], v[108:109]
	s_waitcnt vmcnt(15)
	v_pk_mul_f32 v[34:35], v[34:35], v[208:209]
	v_pk_mul_f32 v[36:37], v[36:37], v[210:211]
	global_store_dwordx4 v[110:111], v[34:37], off nt
	v_pk_fma_f32 v[104:105], v[76:77], v[76:77], v[118:119]
	v_pk_fma_f32 v[110:111], v[50:51], v[50:51], v[112:113]
	v_pk_fma_f32 v[112:113], v[102:103], v[102:103], v[114:115]
	v_pk_fma_f32 v[106:107], v[72:73], v[72:73], v[120:121]
	v_pk_fma_f32 v[104:105], v[96:97], v[96:97], v[104:105]
	v_pk_add_f32 v[38:39], v[112:113], v[38:39]
	v_pk_fma_f32 v[106:107], v[94:95], v[94:95], v[106:107]
	v_pk_add_f32 v[38:39], v[38:39], v[104:105]
	v_mov_b32_e32 v112, v110
	v_mov_b32_e32 v113, v40
	v_pk_add_f32 v[38:39], v[38:39], v[106:107]
	v_mov_b32_e32 v40, v111
	v_pk_add_f32 v[38:39], v[38:39], v[112:113]
	v_mov_b32_e32 v110, v108
	v_mov_b32_e32 v111, v42
	v_pk_add_f32 v[38:39], v[38:39], v[40:41]
	v_mov_b32_e32 v42, v109
	v_pk_add_f32 v[38:39], v[38:39], v[110:111]
	s_nop 0
	v_pk_add_f32 v[38:39], v[38:39], v[42:43]
	ds_bpermute_b32 v41, v132, v39
	ds_bpermute_b32 v40, v132, v38
	v_lshl_add_u64 v[42:43], s[20:21], 0, v[32:33]
	v_mov_b32_e32 v32, v91
	v_mov_b32_e32 v33, v103
	v_lshl_add_u64 v[104:105], v[42:43], 0, v[6:7]
	s_waitcnt lgkmcnt(0)
	v_pk_add_f32 v[38:39], v[38:39], v[40:41]
	ds_bpermute_b32 v41, v133, v39
	ds_bpermute_b32 v40, v133, v38
	v_mov_b32_e32 v91, v102
	s_waitcnt lgkmcnt(0)
	v_pk_add_f32 v[38:39], v[38:39], v[40:41]
	ds_bpermute_b32 v41, v134, v39
	ds_bpermute_b32 v40, v134, v38
	s_waitcnt lgkmcnt(0)
	v_pk_add_f32 v[38:39], v[38:39], v[40:41]
	ds_bpermute_b32 v41, v135, v39
	ds_bpermute_b32 v40, v135, v38
	s_waitcnt lgkmcnt(0)
	v_pk_add_f32 v[38:39], v[38:39], v[40:41]
	ds_bpermute_b32 v41, v136, v39
	ds_bpermute_b32 v40, v136, v38
	s_waitcnt lgkmcnt(0)
	v_pk_add_f32 v[38:39], v[38:39], v[40:41]
	ds_bpermute_b32 v41, v137, v39
	ds_bpermute_b32 v40, v137, v38
	s_waitcnt lgkmcnt(0)
	v_pk_add_f32 v[38:39], v[38:39], v[40:41]
	s_nop 0
	v_pk_fma_f32 v[38:39], v[38:39], s[2:3], v[28:29] op_sel_hi:[1,0,0]
	v_mov_b32_e32 v40, v71
	v_mul_f32_e32 v5, 0x4b800000, v39
	v_cmp_gt_f32_e32 vcc, s4, v39
	v_mov_b32_e32 v41, v87
	v_mov_b32_e32 v71, v86
	v_cndmask_b32_e32 v5, v39, v5, vcc
	v_rsq_f32_e32 v5, v5
	s_nop 0
	v_mul_f32_e32 v39, 0x45800000, v5
	v_cndmask_b32_e32 v106, v5, v39, vcc
	v_pk_mul_f32 v[108:109], v[32:33], v[106:107] op_sel_hi:[1,0]
	v_pk_mul_f32 v[32:33], v[40:41], v[106:107] op_sel_hi:[1,0]
	v_mov_b32_e32 v40, v65
	v_mov_b32_e32 v41, v75
	s_waitcnt vmcnt(16)
	v_pk_mul_f32 v[32:33], v[180:181], v[32:33]
	v_pk_mul_f32 v[34:35], v[182:183], v[108:109]
	global_store_dwordx4 v[104:105], v[32:35], off nt
	v_mov_b32_e32 v36, v89
	v_mov_b32_e32 v37, v101
	v_pk_mul_f32 v[36:37], v[36:37], v[106:107] op_sel_hi:[1,0]
	v_pk_mul_f32 v[40:41], v[40:41], v[106:107] op_sel_hi:[1,0]
	v_mul_f32_e32 v5, 0x4b800000, v38
	v_cmp_gt_f32_e32 vcc, s4, v38
	v_mov_b32_e32 v65, v74
	v_mov_b32_e32 v89, v100
	v_cndmask_b32_e32 v5, v38, v5, vcc
	v_rsq_f32_e32 v5, v5
	s_waitcnt vmcnt(17)
	v_pk_mul_f32 v[32:33], v[184:185], v[40:41]
	v_pk_mul_f32 v[34:35], v[186:187], v[36:37]
	global_store_dwordx4 v[104:105], v[32:35], off offset:1024 nt
	v_mov_b32_e32 v36, v77
	v_mov_b32_e32 v37, v97
	v_mov_b32_e32 v40, v61
	v_mov_b32_e32 v41, v63
	v_pk_mul_f32 v[36:37], v[36:37], v[106:107] op_sel_hi:[1,0]
	v_pk_mul_f32 v[40:41], v[40:41], v[106:107] op_sel_hi:[1,0]
	v_mov_b32_e32 v61, v62
	v_mov_b32_e32 v77, v96
	s_waitcnt vmcnt(18)
	v_pk_mul_f32 v[32:33], v[188:189], v[40:41]
	v_pk_mul_f32 v[34:35], v[190:191], v[36:37]
	global_store_dwordx4 v[104:105], v[32:35], off offset:2048 nt
	v_mov_b32_e32 v36, v73
	v_mov_b32_e32 v37, v95
	v_mov_b32_e32 v40, v57
	v_mov_b32_e32 v41, v59
	v_pk_mul_f32 v[36:37], v[36:37], v[106:107] op_sel_hi:[1,0]
	v_pk_mul_f32 v[40:41], v[40:41], v[106:107] op_sel_hi:[1,0]
	v_mov_b32_e32 v57, v58
	v_mov_b32_e32 v73, v94
	s_waitcnt vmcnt(19)
	v_pk_mul_f32 v[32:33], v[192:193], v[40:41]
	v_pk_mul_f32 v[34:35], v[194:195], v[36:37]
	global_store_dwordx4 v[104:105], v[32:35], off offset:3072 nt
	v_mov_b32_e32 v40, v92
	v_mov_b32_e32 v41, v98
	v_mov_b32_e32 v104, v84
	v_mov_b32_e32 v105, v80
	v_pk_mul_f32 v[40:41], v[40:41], v[106:107] op_sel_hi:[1,0]
	v_pk_mul_f32 v[104:105], v[104:105], v[106:107] op_sel_hi:[1,0]
	v_lshl_add_u64 v[36:37], v[42:43], 0, v[20:21]
	v_mov_b32_e32 v80, v85
	v_mov_b32_e32 v98, v93
	v_pk_mul_f32 v[80:81], v[80:81], v[106:107] op_sel_hi:[1,0]
	s_waitcnt vmcnt(20)
	v_pk_mul_f32 v[32:33], v[196:197], v[104:105]
	v_pk_mul_f32 v[34:35], v[198:199], v[40:41]
	global_store_dwordx4 v[36:37], v[32:35], off nt
	v_pk_mul_f32 v[40:41], v[98:99], v[106:107] op_sel_hi:[1,0]
	v_lshl_add_u64 v[36:37], v[42:43], 0, v[22:23]
	s_waitcnt vmcnt(21)
	v_pk_mul_f32 v[32:33], v[200:201], v[80:81]
	v_pk_mul_f32 v[34:35], v[202:203], v[40:41]
	global_store_dwordx4 v[36:37], v[32:35], off nt
	v_mov_b32_e32 v40, v82
	v_mov_b32_e32 v41, v78
	v_mov_b32_e32 v80, v66
	v_mov_b32_e32 v81, v68
	v_pk_mul_f32 v[40:41], v[40:41], v[106:107] op_sel_hi:[1,0]
	v_pk_mul_f32 v[80:81], v[80:81], v[106:107] op_sel_hi:[1,0]
	v_lshl_add_u64 v[36:37], v[42:43], 0, v[24:25]
	v_mov_b32_e32 v68, v67
	v_mov_b32_e32 v78, v83
	s_waitcnt vmcnt(22)
	v_pk_mul_f32 v[32:33], v[80:81], v[204:205]
	v_pk_mul_f32 v[34:35], v[40:41], v[206:207]
	global_store_dwordx4 v[36:37], v[32:35], off nt
	v_lshl_add_u64 v[36:37], v[42:43], 0, v[26:27]
	v_pk_mul_f32 v[40:41], v[78:79], v[106:107] op_sel_hi:[1,0]
	v_pk_mul_f32 v[42:43], v[68:69], v[106:107] op_sel_hi:[1,0]
	s_waitcnt vmcnt(23)
	v_pk_mul_f32 v[34:35], v[40:41], v[210:211]
	v_pk_mul_f32 v[32:33], v[42:43], v[208:209]
	global_store_dwordx4 v[36:37], v[32:35], off nt
	v_lshl_add_u64 v[36:37], s[20:21], 0, v[30:31]
	v_mul_f32_e32 v30, 0x45800000, v5
	v_cndmask_b32_e32 v40, v5, v30, vcc
	v_pk_mul_f32 v[42:43], v[90:91], v[40:41] op_sel_hi:[1,0]
	v_pk_mul_f32 v[30:31], v[70:71], v[40:41] op_sel_hi:[1,0]
	v_lshl_add_u64 v[38:39], v[36:37], 0, v[6:7]
	v_and_b32_e32 v247, 32, v4
	v_cmp_eq_u32_e32 vcc, 0, v247
	s_or_b64 s[0:1], vcc, s[0:1]
	s_waitcnt vmcnt(24)
	v_pk_mul_f32 v[30:31], v[180:181], v[30:31]
	v_pk_mul_f32 v[32:33], v[182:183], v[42:43]
	global_store_dwordx4 v[38:39], v[30:33], off nt
	v_pk_mul_f32 v[34:35], v[88:89], v[40:41] op_sel_hi:[1,0]
	v_pk_mul_f32 v[42:43], v[64:65], v[40:41] op_sel_hi:[1,0]
	s_waitcnt vmcnt(25)
	v_pk_mul_f32 v[32:33], v[186:187], v[34:35]
	v_pk_mul_f32 v[30:31], v[184:185], v[42:43]
	global_store_dwordx4 v[38:39], v[30:33], off offset:1024 nt
	v_pk_mul_f32 v[34:35], v[76:77], v[40:41] op_sel_hi:[1,0]
	v_pk_mul_f32 v[42:43], v[60:61], v[40:41] op_sel_hi:[1,0]
	s_waitcnt vmcnt(26)
	v_pk_mul_f32 v[32:33], v[190:191], v[34:35]
	v_pk_mul_f32 v[30:31], v[188:189], v[42:43]
	global_store_dwordx4 v[38:39], v[30:33], off offset:2048 nt
	v_pk_mul_f32 v[34:35], v[72:73], v[40:41] op_sel_hi:[1,0]
	v_pk_mul_f32 v[42:43], v[56:57], v[40:41] op_sel_hi:[1,0]
	s_waitcnt vmcnt(27)
	v_pk_mul_f32 v[32:33], v[194:195], v[34:35]
	v_pk_mul_f32 v[30:31], v[192:193], v[42:43]
	global_store_dwordx4 v[38:39], v[30:33], off offset:3072 nt
	v_mov_b32_e32 v38, v48
	v_mov_b32_e32 v39, v50
	v_mov_b32_e32 v42, v0
	v_mov_b32_e32 v43, v2
	v_pk_mul_f32 v[38:39], v[38:39], v[40:41] op_sel_hi:[1,0]
	v_pk_mul_f32 v[42:43], v[42:43], v[40:41] op_sel_hi:[1,0]
	v_lshl_add_u64 v[34:35], v[36:37], 0, v[20:21]
	v_mov_b32_e32 v2, v1
	v_mov_b32_e32 v50, v49
	v_pk_mul_f32 v[0:1], v[2:3], v[40:41] op_sel_hi:[1,0]
	s_waitcnt vmcnt(28)
	v_pk_mul_f32 v[30:31], v[196:197], v[42:43]
	v_pk_mul_f32 v[32:33], v[198:199], v[38:39]
	global_store_dwordx4 v[34:35], v[30:33], off nt
	v_pk_mul_f32 v[38:39], v[50:51], v[40:41] op_sel_hi:[1,0]
	v_lshl_add_u64 v[34:35], v[36:37], 0, v[22:23]
	s_waitcnt vmcnt(29)
	v_pk_mul_f32 v[0:1], v[200:201], v[0:1]
	v_pk_mul_f32 v[2:3], v[202:203], v[38:39]
	global_store_dwordx4 v[34:35], v[0:3], off nt
	v_mov_b32_e32 v32, v54
	v_mov_b32_e32 v33, v44
	v_mov_b32_e32 v34, v46
	v_mov_b32_e32 v35, v52
	v_pk_mul_f32 v[32:33], v[32:33], v[40:41] op_sel_hi:[1,0]
	v_pk_mul_f32 v[34:35], v[34:35], v[40:41] op_sel_hi:[1,0]
	v_lshl_add_u64 v[30:31], v[36:37], 0, v[24:25]
	v_mov_b32_e32 v52, v47
	v_mov_b32_e32 v44, v55
	s_waitcnt vmcnt(30)
	v_pk_mul_f32 v[0:1], v[34:35], v[204:205]
	v_pk_mul_f32 v[2:3], v[32:33], v[206:207]
	global_store_dwordx4 v[30:31], v[0:3], off nt
	v_pk_mul_f32 v[32:33], v[44:45], v[40:41] op_sel_hi:[1,0]
	v_pk_mul_f32 v[34:35], v[52:53], v[40:41] op_sel_hi:[1,0]
	v_lshl_add_u64 v[30:31], v[36:37], 0, v[26:27]
	s_waitcnt vmcnt(31)
	v_pk_mul_f32 v[0:1], v[34:35], v[208:209]
	v_pk_mul_f32 v[2:3], v[32:33], v[210:211]
	global_store_dwordx4 v[30:31], v[0:3], off nt
	s_andn2_b64 exec, exec, s[0:1]
	s_cbranch_execnz .LBB0_1348
